# retention out-unit epilogue gate tile staged through a wave-private LDS image with whole-line HBM accesses (instead of 32-byte pieces); otherwise as previous (P0 nt loads, conv on GLU-idle WGs, scan r
# baseline (speedup 1.0000x reference)
.LBB0_562:
	s_lshl_b32 s8, s16, 5
	s_and_b32 s8, s8, 0xffffff00
	v_add_u32_e32 v128, s8, v209
	v_ashrrev_i32_e32 v129, 31, v128
	v_lshlrev_b64 v[128:129], 12, v[128:129]
	v_lshl_add_u64 v[128:129], s[4:5], 0, v[128:129]
	s_lshl_b32 s96, s24, 9
	v_lshl_add_u64 v[128:129], v[128:129], 0, s[96:97]
	v_readfirstlane_b32 s82, v209
	v_and_b32_e32 v180, 31, v209
	v_lshrrev_b32_e32 v181, 2, v208
	v_sub_u32_e32 v182, v181, v180
	v_ashrrev_i32_e32 v183, 31, v182
	s_mul_i32 s82, s82, 0x210
	s_mov_b64 s[84:85], 0x2000
	v_lshlrev_b64 v[182:183], 12, v[182:183]
	v_lshl_add_u64 v[184:185], v[128:129], 0, v[182:183]
	v_lshlrev_b32_e32 v182, 4, v180
	v_mov_b32_e32 v183, 0
	v_lshl_add_u64 v[184:185], v[184:185], 0, v[182:183]
	v_mul_u32_u24_e32 v206, 0x210, v180
	v_lshl_add_u32 v206, v181, 4, v206
	v_add_u32_e32 v206, s82, v206
	v_mul_u32_u24_e32 v207, 0x210, v181
	v_lshl_add_u32 v207, v180, 4, v207
	v_add_u32_e32 v207, s82, v207
	v_mov_b64_e32 v[178:179], v[184:185]
	global_load_dwordx4 v[188:191], v[178:179], off
	v_lshl_add_u64 v[178:179], v[178:179], 0, s[84:85]
	global_load_dwordx4 v[192:195], v[178:179], off
	v_lshl_add_u64 v[178:179], v[178:179], 0, s[84:85]
	global_load_dwordx4 v[196:199], v[178:179], off
	v_lshl_add_u64 v[178:179], v[178:179], 0, s[84:85]
	global_load_dwordx4 v[202:205], v[178:179], off
	v_lshl_add_u64 v[178:179], v[178:179], 0, s[84:85]
	global_load_dwordx4 v[210:213], v[178:179], off
	v_lshl_add_u64 v[178:179], v[178:179], 0, s[84:85]
	global_load_dwordx4 v[216:219], v[178:179], off
	v_lshl_add_u64 v[178:179], v[178:179], 0, s[84:85]
	global_load_dwordx4 v[220:223], v[178:179], off
	v_lshl_add_u64 v[178:179], v[178:179], 0, s[84:85]
	global_load_dwordx4 v[224:227], v[178:179], off
	v_lshl_add_u64 v[178:179], v[178:179], 0, s[84:85]
	global_load_dwordx4 v[238:241], v[178:179], off
	v_lshl_add_u64 v[178:179], v[178:179], 0, s[84:85]
	global_load_dwordx4 v[242:245], v[178:179], off
	v_lshl_add_u64 v[178:179], v[178:179], 0, s[84:85]
	global_load_dwordx4 v[246:249], v[178:179], off
	v_lshl_add_u64 v[178:179], v[178:179], 0, s[84:85]
	global_load_dwordx4 v[230:233], v[178:179], off
	v_lshl_add_u64 v[178:179], v[178:179], 0, s[84:85]
	global_load_dwordx4 v[148:151], v[178:179], off
	v_lshl_add_u64 v[178:179], v[178:179], 0, s[84:85]
	global_load_dwordx4 v[152:155], v[178:179], off
	v_lshl_add_u64 v[178:179], v[178:179], 0, s[84:85]
	global_load_dwordx4 v[166:169], v[178:179], off
	v_lshl_add_u64 v[178:179], v[178:179], 0, s[84:85]
	global_load_dwordx4 v[170:173], v[178:179], off
	v_mul_f32_e32 v132, v113, v113
	v_fmac_f32_e32 v132, v112, v112
	v_fmac_f32_e32 v132, v114, v114
	v_fmac_f32_e32 v132, v115, v115
	v_fmac_f32_e32 v132, v116, v116
	v_fmac_f32_e32 v132, v117, v117
	v_fmac_f32_e32 v132, v118, v118
	v_fmac_f32_e32 v132, v119, v119
	v_fmac_f32_e32 v132, v120, v120
	v_fmac_f32_e32 v132, v121, v121
	v_fmac_f32_e32 v132, v122, v122
	v_fmac_f32_e32 v132, v123, v123
	v_fmac_f32_e32 v132, v124, v124
	v_fmac_f32_e32 v132, v125, v125
	v_fmac_f32_e32 v132, v126, v126
	v_fmac_f32_e32 v132, v127, v127
	v_fmac_f32_e32 v132, v96, v96
	v_fmac_f32_e32 v132, v97, v97
	v_fmac_f32_e32 v132, v98, v98
	v_fmac_f32_e32 v132, v99, v99
	v_fmac_f32_e32 v132, v100, v100
	v_fmac_f32_e32 v132, v101, v101
	v_fmac_f32_e32 v132, v102, v102
	v_fmac_f32_e32 v132, v103, v103
	v_fmac_f32_e32 v132, v104, v104
	v_fmac_f32_e32 v132, v105, v105
	v_fmac_f32_e32 v132, v106, v106
	v_fmac_f32_e32 v132, v107, v107
	v_fmac_f32_e32 v132, v108, v108
	v_fmac_f32_e32 v132, v109, v109
	v_fmac_f32_e32 v132, v110, v110
	v_fmac_f32_e32 v132, v111, v111
	v_fmac_f32_e32 v132, v80, v80
	v_fmac_f32_e32 v132, v81, v81
	v_fmac_f32_e32 v132, v82, v82
	v_fmac_f32_e32 v132, v83, v83
	v_fmac_f32_e32 v132, v84, v84
	v_fmac_f32_e32 v132, v85, v85
	v_fmac_f32_e32 v132, v86, v86
	v_fmac_f32_e32 v132, v87, v87
	v_fmac_f32_e32 v132, v88, v88
	v_fmac_f32_e32 v132, v89, v89
	v_fmac_f32_e32 v132, v90, v90
	v_fmac_f32_e32 v132, v91, v91
	v_fmac_f32_e32 v132, v92, v92
	v_fmac_f32_e32 v132, v93, v93
	v_fmac_f32_e32 v132, v94, v94
	v_fmac_f32_e32 v132, v95, v95
	v_fmac_f32_e32 v132, v64, v64
	v_fmac_f32_e32 v132, v65, v65
	v_fmac_f32_e32 v132, v66, v66
	v_fmac_f32_e32 v132, v67, v67
	v_fmac_f32_e32 v132, v68, v68
	v_fmac_f32_e32 v132, v69, v69
	v_fmac_f32_e32 v132, v70, v70
	v_fmac_f32_e32 v132, v71, v71
	v_fmac_f32_e32 v132, v72, v72
	v_fmac_f32_e32 v132, v73, v73
	v_fmac_f32_e32 v132, v74, v74
	v_fmac_f32_e32 v132, v75, v75
	v_fmac_f32_e32 v132, v76, v76
	v_fmac_f32_e32 v132, v77, v77
	v_fmac_f32_e32 v132, v78, v78
	v_fmac_f32_e32 v132, v79, v79
	v_fmac_f32_e32 v132, v48, v48
	v_fmac_f32_e32 v132, v49, v49
	v_fmac_f32_e32 v132, v50, v50
	v_fmac_f32_e32 v132, v51, v51
	v_fmac_f32_e32 v132, v52, v52
	v_fmac_f32_e32 v132, v53, v53
	v_fmac_f32_e32 v132, v54, v54
	v_fmac_f32_e32 v132, v55, v55
	v_fmac_f32_e32 v132, v56, v56
	v_fmac_f32_e32 v132, v57, v57
	v_fmac_f32_e32 v132, v58, v58
	v_fmac_f32_e32 v132, v59, v59
	v_fmac_f32_e32 v132, v60, v60
	v_fmac_f32_e32 v132, v61, v61
	v_fmac_f32_e32 v132, v62, v62
	v_fmac_f32_e32 v132, v63, v63
	s_movk_i32 s8, 0xe0
	v_ashrrev_i32_e32 v209, 31, v208
	v_fmac_f32_e32 v132, v32, v32
	s_load_dwordx2 s[8:9], s[10:11], s8
	s_waitcnt lgkmcnt(0)
	v_lshl_add_u64 v[144:145], v[208:209], 1, v[128:129]
	v_fmac_f32_e32 v132, v33, v33
	s_barrier
	s_waitcnt vmcnt(15)
	ds_write_b128 v207, v[188:191]
	s_waitcnt vmcnt(14)
	ds_write_b128 v207, v[192:195] offset:1056
	s_waitcnt vmcnt(13)
	ds_write_b128 v207, v[196:199] offset:2112
	s_waitcnt vmcnt(12)
	ds_write_b128 v207, v[202:205] offset:3168
	s_waitcnt vmcnt(11)
	ds_write_b128 v207, v[210:213] offset:4224
	s_waitcnt vmcnt(10)
	ds_write_b128 v207, v[216:219] offset:5280
	s_waitcnt vmcnt(9)
	ds_write_b128 v207, v[220:223] offset:6336
	s_waitcnt vmcnt(8)
	ds_write_b128 v207, v[224:227] offset:7392
	s_waitcnt vmcnt(7)
	ds_write_b128 v207, v[238:241] offset:8448
	s_waitcnt vmcnt(6)
	ds_write_b128 v207, v[242:245] offset:9504
	s_waitcnt vmcnt(5)
	ds_write_b128 v207, v[246:249] offset:10560
	s_waitcnt vmcnt(4)
	ds_write_b128 v207, v[230:233] offset:11616
	s_waitcnt vmcnt(3)
	ds_write_b128 v207, v[148:151] offset:12672
	s_waitcnt vmcnt(2)
	ds_write_b128 v207, v[152:155] offset:13728
	s_waitcnt vmcnt(1)
	ds_write_b128 v207, v[166:169] offset:14784
	s_waitcnt vmcnt(0)
	ds_write_b128 v207, v[170:173] offset:15840
	s_waitcnt lgkmcnt(8)
	s_waitcnt lgkmcnt(0)
	ds_read_b128 v[188:191], v206 offset:0
	ds_read_b128 v[192:195], v206 offset:32
	ds_read_b128 v[196:199], v206 offset:64
	ds_read_b128 v[202:205], v206 offset:96
	ds_read_b128 v[210:213], v206 offset:128
	ds_read_b128 v[216:219], v206 offset:160
	ds_read_b128 v[220:223], v206 offset:192
	ds_read_b128 v[224:227], v206 offset:224
	v_fmac_f32_e32 v132, v34, v34
	v_fmac_f32_e32 v132, v35, v35
	v_fmac_f32_e32 v132, v36, v36
	v_fmac_f32_e32 v132, v37, v37
	v_fmac_f32_e32 v132, v38, v38
	v_fmac_f32_e32 v132, v39, v39
	v_fmac_f32_e32 v132, v40, v40
	v_fmac_f32_e32 v132, v41, v41
	v_fmac_f32_e32 v132, v42, v42
	v_fmac_f32_e32 v132, v43, v43
	v_fmac_f32_e32 v132, v44, v44
	s_add_u32 s8, s8, s14
	v_fmac_f32_e32 v132, v45, v45
	s_addc_u32 s9, s9, s15
	s_lshl_b32 s17, s24, 10
	v_fmac_f32_e32 v132, v46, v46
	s_add_u32 s8, s8, s17
	v_fmac_f32_e32 v132, v47, v47
	s_addc_u32 s9, s9, 0
	v_fmac_f32_e32 v132, v16, v16
	v_lshl_add_u64 v[146:147], v[208:209], 2, s[8:9]
	v_fmac_f32_e32 v132, v17, v17
	global_load_dwordx4 v[158:161], v[146:147], off
	global_load_dwordx4 v[162:165], v[146:147], off offset:32
	v_fmac_f32_e32 v132, v18, v18
	v_fmac_f32_e32 v132, v19, v19
	v_fmac_f32_e32 v132, v20, v20
	v_fmac_f32_e32 v132, v21, v21
	v_fmac_f32_e32 v132, v22, v22
	v_fmac_f32_e32 v132, v23, v23
	v_fmac_f32_e32 v132, v24, v24
	v_fmac_f32_e32 v132, v25, v25
	v_fmac_f32_e32 v132, v26, v26
	v_fmac_f32_e32 v132, v27, v27
	v_fmac_f32_e32 v132, v28, v28
	v_fmac_f32_e32 v132, v29, v29
	v_fmac_f32_e32 v132, v30, v30
	v_fmac_f32_e32 v132, v31, v31
	v_fmac_f32_e32 v132, v0, v0
	v_fmac_f32_e32 v132, v1, v1
	v_fmac_f32_e32 v132, v2, v2
	v_fmac_f32_e32 v132, v3, v3
	v_fmac_f32_e32 v132, v4, v4
	v_fmac_f32_e32 v132, v5, v5
	v_fmac_f32_e32 v132, v6, v6
	v_fmac_f32_e32 v132, v7, v7
	v_fmac_f32_e32 v132, v8, v8
	v_fmac_f32_e32 v132, v9, v9
	v_fmac_f32_e32 v132, v10, v10
	v_fmac_f32_e32 v132, v11, v11
	v_pk_mul_f32 v[130:131], v[12:13], v[12:13]
	v_pk_mul_f32 v[128:129], v[14:15], v[14:15]
	v_add_f32_e32 v130, v130, v132
	v_add_f32_e32 v130, v131, v130
	v_add_f32_e32 v128, v128, v130
	v_add_f32_e32 v128, v129, v128
	v_xor_b32_e32 v129, 0x80, v214
	ds_bpermute_b32 v129, v129, v128
	s_waitcnt lgkmcnt(8)
	v_permlane32_swap_b32_e32 v188, v190
	v_permlane32_swap_b32_e32 v189, v191
	s_waitcnt lgkmcnt(7)
	v_permlane32_swap_b32_e32 v192, v194
	v_permlane32_swap_b32_e32 v193, v195
	s_waitcnt lgkmcnt(6)
	v_permlane32_swap_b32_e32 v196, v198
	v_permlane32_swap_b32_e32 v197, v199
	s_waitcnt lgkmcnt(5)
	v_permlane32_swap_b32_e32 v202, v204
	v_permlane32_swap_b32_e32 v203, v205
	v_mov_b64_e32 v[174:175], v[188:189]
	v_mov_b64_e32 v[176:177], v[190:191]
	v_mov_b64_e32 v[178:179], v[192:193]
	v_mov_b64_e32 v[180:181], v[194:195]
	v_mov_b64_e32 v[154:155], v[196:197]
	v_mov_b64_e32 v[152:153], v[198:199]
	v_mov_b64_e32 v[150:151], v[202:203]
	v_mov_b64_e32 v[148:149], v[204:205]
	global_load_dwordx4 v[166:169], v[146:147], off offset:64
	global_load_dwordx4 v[170:173], v[146:147], off offset:96
	global_load_dwordx4 v[140:143], v[146:147], off offset:128
	global_load_dwordx4 v[136:139], v[146:147], off offset:160
	s_add_i32 s16, s16, s48
	s_add_u32 s12, s12, s26
	s_addc_u32 s13, s13, s27
	s_waitcnt lgkmcnt(0)
	v_add_f32_e32 v128, v128, v129
	v_fmamk_f32 v128, v128, 0x3b800000, v228
	v_mul_f32_e32 v129, 0x4f800000, v128
	v_cmp_gt_f32_e32 vcc, s1, v128
	s_cmpk_gt_i32 s16, 0xff
	v_lshlrev_b32_e32 v157, 16, v174
	v_cndmask_b32_e32 v128, v128, v129, vcc
	v_sqrt_f32_e32 v129, v128
	v_and_b32_e32 v174, 0xffff0000, v174
	v_mul_f32_e32 v183, 0xbfb8aa3b, v174
	v_exp_f32_e32 v183, v183
	v_add_u32_e32 v130, -1, v129
	v_fma_f32 v131, -v130, v129, v128
	v_cmp_ge_f32_e64 s[8:9], 0, v131
	v_add_u32_e32 v131, 1, v129
	s_nop 0
	v_cndmask_b32_e64 v130, v129, v130, s[8:9]
	v_fma_f32 v129, -v131, v129, v128
	v_cmp_lt_f32_e64 s[8:9], 0, v129
	s_nop 1
	v_cndmask_b32_e64 v129, v130, v131, s[8:9]
	v_mul_f32_e32 v130, 0x37800000, v129
	v_cndmask_b32_e32 v129, v129, v130, vcc
	v_cmp_class_f32_e32 vcc, v128, v229
	s_nop 1
	v_cndmask_b32_e32 v128, v129, v128, vcc
	v_div_scale_f32 v129, s[8:9], v128, v128, 1.0
	v_rcp_f32_e32 v130, v129
	s_nop 0
	v_fma_f32 v131, -v129, v130, 1.0
	v_fmac_f32_e32 v130, v131, v130
	v_div_scale_f32 v131, vcc, 1.0, v128, 1.0
	v_mul_f32_e32 v132, v131, v130
	v_fma_f32 v133, -v129, v132, v131
	v_fmac_f32_e32 v132, v133, v130
	v_fma_f32 v129, -v129, v132, v131
	v_div_fmas_f32 v129, v129, v130, v132
	v_div_fixup_f32 v156, v129, v128, 1.0
	v_mul_f32_e32 v128, 0xbfb8aa3b, v157
	v_exp_f32_e32 v182, v128
	global_load_dwordx4 v[132:135], v[146:147], off offset:192
	global_load_dwordx4 v[128:131], v[146:147], off offset:224
	v_add_f32_e32 v182, 1.0, v182
	v_rcp_f32_e32 v182, v182
	s_nop 0
	v_mul_f32_e32 v157, v182, v157
	v_mul_f32_e32 v112, v112, v157
	v_add_f32_e32 v157, 1.0, v183
	v_rcp_f32_e32 v157, v157
	v_mul_f32_e32 v112, v156, v112
	v_lshlrev_b32_e32 v182, 16, v175
	v_mul_f32_e32 v183, 0xbfb8aa3b, v182
	s_waitcnt vmcnt(7)
	v_mul_f32_e32 v112, v158, v112
	v_and_b32_e32 v158, 0xffff0000, v175
	v_exp_f32_e32 v183, v183
	v_mul_f32_e32 v157, v157, v174
	v_mul_f32_e32 v174, 0xbfb8aa3b, v158
	v_exp_f32_e32 v174, v174
	v_mul_f32_e32 v113, v113, v157
	v_add_f32_e32 v157, 1.0, v183
	v_mul_f32_e32 v113, v156, v113
	v_rcp_f32_e32 v157, v157
	v_mul_f32_e32 v113, v159, v113
	v_add_f32_e32 v159, 1.0, v174
	v_rcp_f32_e32 v159, v159
	v_mul_f32_e32 v157, v157, v182
	v_mul_f32_e32 v114, v114, v157
	v_mul_f32_e32 v114, v156, v114
	v_mul_f32_e32 v157, v159, v158
	v_mul_f32_e32 v115, v115, v157
	v_lshlrev_b32_e32 v157, 16, v176
	v_mul_f32_e32 v158, 0xbfb8aa3b, v157
	v_exp_f32_e32 v158, v158
	v_mul_f32_e32 v115, v156, v115
	v_mul_f32_e32 v114, v160, v114
	v_mul_f32_e32 v115, v161, v115
	v_cvt_pk_bf16_f32 v112, v112, v113
	v_cvt_pk_bf16_f32 v113, v114, v115
	v_mov_b64_e32 v[238:239], v[112:113]
	v_add_f32_e32 v112, 1.0, v158
	v_and_b32_e32 v113, 0xffff0000, v176
	v_rcp_f32_e32 v112, v112
	v_mul_f32_e32 v114, 0xbfb8aa3b, v113
	v_exp_f32_e32 v114, v114
	v_lshlrev_b32_e32 v115, 16, v177
	v_mul_f32_e32 v112, v112, v157
	v_mul_f32_e32 v112, v116, v112
	v_add_f32_e32 v114, 1.0, v114
	v_mul_f32_e32 v116, 0xbfb8aa3b, v115
	v_rcp_f32_e32 v114, v114
	v_exp_f32_e32 v116, v116
	v_mul_f32_e32 v112, v156, v112
	s_waitcnt vmcnt(6)
	v_mul_f32_e32 v112, v162, v112
	v_mul_f32_e32 v113, v114, v113
	v_add_f32_e32 v114, 1.0, v116
	v_and_b32_e32 v116, 0xffff0000, v177
	v_mul_f32_e32 v113, v117, v113
	v_mul_f32_e32 v117, 0xbfb8aa3b, v116
	v_rcp_f32_e32 v114, v114
	v_exp_f32_e32 v117, v117
	v_mul_f32_e32 v113, v156, v113
	v_mul_f32_e32 v113, v163, v113
	v_mul_f32_e32 v114, v114, v115
	v_add_f32_e32 v115, 1.0, v117
	v_rcp_f32_e32 v115, v115
	v_mul_f32_e32 v114, v118, v114
	v_mul_f32_e32 v114, v156, v114
	v_mul_f32_e32 v114, v164, v114
	v_mul_f32_e32 v115, v115, v116
	v_lshlrev_b32_e32 v116, 16, v178
	v_mul_f32_e32 v117, 0xbfb8aa3b, v116
	v_mul_f32_e32 v115, v119, v115
	v_exp_f32_e32 v117, v117
	v_mul_f32_e32 v115, v156, v115
	v_mul_f32_e32 v115, v165, v115
	v_cvt_pk_bf16_f32 v112, v112, v113
	v_cvt_pk_bf16_f32 v113, v114, v115
	v_mov_b64_e32 v[240:241], v[112:113]
	s_nop 1
	v_permlane32_swap_b32_e32 v238, v240
	v_permlane32_swap_b32_e32 v239, v241
	ds_write_b128 v206, v[238:241] offset:0
	v_and_b32_e32 v113, 0xffff0000, v178
	v_add_f32_e32 v112, 1.0, v117
	v_mul_f32_e32 v114, 0xbfb8aa3b, v113
	v_rcp_f32_e32 v112, v112
	v_exp_f32_e32 v114, v114
	v_lshlrev_b32_e32 v115, 16, v179
	v_mul_f32_e32 v112, v112, v116
	v_add_f32_e32 v114, 1.0, v114
	v_mul_f32_e32 v116, 0xbfb8aa3b, v115
	v_rcp_f32_e32 v114, v114
	v_exp_f32_e32 v116, v116
	v_mul_f32_e32 v112, v120, v112
	v_mul_f32_e32 v112, v156, v112
	v_mul_f32_e32 v113, v114, v113
	v_add_f32_e32 v114, 1.0, v116
	v_and_b32_e32 v116, 0xffff0000, v179
	v_mul_f32_e32 v117, 0xbfb8aa3b, v116
	v_rcp_f32_e32 v114, v114
	v_exp_f32_e32 v117, v117
	v_mul_f32_e32 v113, v121, v113
	v_mul_f32_e32 v113, v156, v113
	v_mul_f32_e32 v114, v114, v115
	v_add_f32_e32 v115, 1.0, v117
	v_rcp_f32_e32 v115, v115
	v_mul_f32_e32 v114, v122, v114
	s_waitcnt vmcnt(5)
	v_mul_f32_e32 v112, v166, v112
	v_mul_f32_e32 v113, v167, v113
	v_mul_f32_e32 v115, v115, v116
	v_lshlrev_b32_e32 v116, 16, v180
	v_mul_f32_e32 v117, 0xbfb8aa3b, v116
	v_mul_f32_e32 v115, v123, v115
	v_exp_f32_e32 v117, v117
	v_mul_f32_e32 v114, v156, v114
	v_mul_f32_e32 v115, v156, v115
	v_mul_f32_e32 v114, v168, v114
	v_mul_f32_e32 v115, v169, v115
	v_cvt_pk_bf16_f32 v112, v112, v113
	v_cvt_pk_bf16_f32 v113, v114, v115
	v_mov_b64_e32 v[242:243], v[112:113]
	v_and_b32_e32 v113, 0xffff0000, v180
	v_add_f32_e32 v112, 1.0, v117
	v_mul_f32_e32 v114, 0xbfb8aa3b, v113
	v_rcp_f32_e32 v112, v112
	v_exp_f32_e32 v114, v114
	v_lshlrev_b32_e32 v115, 16, v181
	v_mul_f32_e32 v112, v112, v116
	v_add_f32_e32 v114, 1.0, v114
	v_mul_f32_e32 v116, 0xbfb8aa3b, v115
	v_rcp_f32_e32 v114, v114
	v_exp_f32_e32 v116, v116
	v_mul_f32_e32 v112, v124, v112
	v_mul_f32_e32 v112, v156, v112
	v_mul_f32_e32 v113, v114, v113
	v_add_f32_e32 v114, 1.0, v116
	v_and_b32_e32 v116, 0xffff0000, v181
	v_mul_f32_e32 v117, 0xbfb8aa3b, v116
	v_rcp_f32_e32 v114, v114
	v_exp_f32_e32 v117, v117
	v_mul_f32_e32 v113, v125, v113
	v_mul_f32_e32 v113, v156, v113
	v_mul_f32_e32 v114, v114, v115
	v_add_f32_e32 v115, 1.0, v117
	v_rcp_f32_e32 v115, v115
	v_mul_f32_e32 v114, v126, v114
	s_waitcnt vmcnt(4)
	v_mul_f32_e32 v112, v170, v112
	v_mul_f32_e32 v113, v171, v113
	v_mul_f32_e32 v115, v115, v116
	v_lshlrev_b32_e32 v116, 16, v154
	v_mul_f32_e32 v117, 0xbfb8aa3b, v116
	v_exp_f32_e32 v117, v117
	v_mul_f32_e32 v115, v127, v115
	v_mul_f32_e32 v114, v156, v114
	v_mul_f32_e32 v115, v156, v115
	v_mul_f32_e32 v114, v172, v114
	v_mul_f32_e32 v115, v173, v115
	v_cvt_pk_bf16_f32 v112, v112, v113
	v_cvt_pk_bf16_f32 v113, v114, v115
	v_mov_b64_e32 v[244:245], v[112:113]
	s_nop 1
	v_permlane32_swap_b32_e32 v242, v244
	v_permlane32_swap_b32_e32 v243, v245
	ds_write_b128 v206, v[242:245] offset:32
	v_add_f32_e32 v112, 1.0, v117
	v_and_b32_e32 v113, 0xffff0000, v154
	v_rcp_f32_e32 v112, v112
	v_mul_f32_e32 v114, 0xbfb8aa3b, v113
	v_exp_f32_e32 v114, v114
	v_mul_f32_e32 v112, v112, v116
	v_mul_f32_e32 v96, v96, v112
	v_add_f32_e32 v112, 1.0, v114
	v_lshlrev_b32_e32 v114, 16, v155
	v_rcp_f32_e32 v112, v112
	v_mul_f32_e32 v115, 0xbfb8aa3b, v114
	v_exp_f32_e32 v115, v115
	v_mul_f32_e32 v96, v156, v96
	v_mul_f32_e32 v112, v112, v113
	v_and_b32_e32 v113, 0xffff0000, v155
	v_mul_f32_e32 v97, v97, v112
	v_add_f32_e32 v112, 1.0, v115
	v_mul_f32_e32 v115, 0xbfb8aa3b, v113
	v_rcp_f32_e32 v112, v112
	v_exp_f32_e32 v115, v115
	v_mul_f32_e32 v97, v156, v97
	s_waitcnt vmcnt(3)
	v_mul_f32_e32 v96, v140, v96
	v_mul_f32_e32 v112, v112, v114
	v_add_f32_e32 v114, 1.0, v115
	v_rcp_f32_e32 v114, v114
	v_mul_f32_e32 v98, v98, v112
	v_mul_f32_e32 v97, v141, v97
	v_mul_f32_e32 v98, v156, v98
	v_mul_f32_e32 v112, v114, v113
	v_mul_f32_e32 v99, v99, v112
	v_lshlrev_b32_e32 v112, 16, v152
	v_mul_f32_e32 v113, 0xbfb8aa3b, v112
	v_exp_f32_e32 v113, v113
	v_mul_f32_e32 v99, v156, v99
	v_mul_f32_e32 v98, v142, v98
	v_mul_f32_e32 v99, v143, v99
	v_cvt_pk_bf16_f32 v96, v96, v97
	v_cvt_pk_bf16_f32 v97, v98, v99
	v_mov_b64_e32 v[246:247], v[96:97]
	v_add_f32_e32 v96, 1.0, v113
	v_and_b32_e32 v97, 0xffff0000, v152
	v_rcp_f32_e32 v96, v96
	v_mul_f32_e32 v98, 0xbfb8aa3b, v97
	v_exp_f32_e32 v98, v98
	v_lshlrev_b32_e32 v99, 16, v153
	v_mul_f32_e32 v96, v96, v112
	v_mul_f32_e32 v96, v100, v96
	v_add_f32_e32 v98, 1.0, v98
	v_mul_f32_e32 v100, 0xbfb8aa3b, v99
	v_rcp_f32_e32 v98, v98
	v_exp_f32_e32 v100, v100
	v_mul_f32_e32 v96, v156, v96
	s_waitcnt vmcnt(2)
	v_mul_f32_e32 v96, v136, v96
	v_mul_f32_e32 v97, v98, v97
	v_add_f32_e32 v98, 1.0, v100
	v_and_b32_e32 v100, 0xffff0000, v153
	v_mul_f32_e32 v97, v101, v97
	v_mul_f32_e32 v101, 0xbfb8aa3b, v100
	v_rcp_f32_e32 v98, v98
	v_exp_f32_e32 v101, v101
	v_mul_f32_e32 v97, v156, v97
	v_mul_f32_e32 v97, v137, v97
	v_mul_f32_e32 v98, v98, v99
	v_add_f32_e32 v99, 1.0, v101
	v_rcp_f32_e32 v99, v99
	v_mul_f32_e32 v98, v102, v98
	v_mul_f32_e32 v98, v156, v98
	v_mul_f32_e32 v98, v138, v98
	v_mul_f32_e32 v99, v99, v100
	v_lshlrev_b32_e32 v100, 16, v150
	v_mul_f32_e32 v101, 0xbfb8aa3b, v100
	v_mul_f32_e32 v99, v103, v99
	v_exp_f32_e32 v101, v101
	v_mul_f32_e32 v99, v156, v99
	v_mul_f32_e32 v99, v139, v99
	v_cvt_pk_bf16_f32 v96, v96, v97
	v_cvt_pk_bf16_f32 v97, v98, v99
	v_mov_b64_e32 v[248:249], v[96:97]
	s_nop 1
	v_permlane32_swap_b32_e32 v246, v248
	v_permlane32_swap_b32_e32 v247, v249
	ds_write_b128 v206, v[246:249] offset:64
	v_and_b32_e32 v97, 0xffff0000, v150
	v_add_f32_e32 v96, 1.0, v101
	v_mul_f32_e32 v98, 0xbfb8aa3b, v97
	v_rcp_f32_e32 v96, v96
	v_exp_f32_e32 v98, v98
	v_lshlrev_b32_e32 v99, 16, v151
	v_mul_f32_e32 v96, v96, v100
	v_add_f32_e32 v98, 1.0, v98
	v_mul_f32_e32 v100, 0xbfb8aa3b, v99
	v_rcp_f32_e32 v98, v98
	v_exp_f32_e32 v100, v100
	v_mul_f32_e32 v96, v104, v96
	v_mul_f32_e32 v96, v156, v96
	v_mul_f32_e32 v97, v98, v97
	v_add_f32_e32 v98, 1.0, v100
	v_and_b32_e32 v100, 0xffff0000, v151
	v_mul_f32_e32 v101, 0xbfb8aa3b, v100
	v_rcp_f32_e32 v98, v98
	v_exp_f32_e32 v101, v101
	v_mul_f32_e32 v97, v105, v97
	v_mul_f32_e32 v97, v156, v97
	v_mul_f32_e32 v98, v98, v99
	v_add_f32_e32 v99, 1.0, v101
	v_rcp_f32_e32 v99, v99
	v_mul_f32_e32 v98, v106, v98
	s_waitcnt vmcnt(1)
	v_mul_f32_e32 v96, v132, v96
	v_mul_f32_e32 v97, v133, v97
	v_mul_f32_e32 v99, v99, v100
	v_lshlrev_b32_e32 v100, 16, v148
	v_mul_f32_e32 v101, 0xbfb8aa3b, v100
	v_mul_f32_e32 v99, v107, v99
	v_exp_f32_e32 v101, v101
	v_mul_f32_e32 v98, v156, v98
	v_mul_f32_e32 v99, v156, v99
	v_mul_f32_e32 v98, v134, v98
	v_mul_f32_e32 v99, v135, v99
	v_cvt_pk_bf16_f32 v96, v96, v97
	v_cvt_pk_bf16_f32 v97, v98, v99
	v_mov_b64_e32 v[230:231], v[96:97]
	v_and_b32_e32 v97, 0xffff0000, v148
	v_add_f32_e32 v96, 1.0, v101
	v_mul_f32_e32 v98, 0xbfb8aa3b, v97
	v_rcp_f32_e32 v96, v96
	v_exp_f32_e32 v98, v98
	v_lshlrev_b32_e32 v99, 16, v149
	v_mul_f32_e32 v96, v96, v100
	v_add_f32_e32 v98, 1.0, v98
	v_mul_f32_e32 v100, 0xbfb8aa3b, v99
	v_rcp_f32_e32 v98, v98
	v_exp_f32_e32 v100, v100
	v_mul_f32_e32 v96, v108, v96
	v_mul_f32_e32 v96, v156, v96
	v_mul_f32_e32 v97, v98, v97
	v_add_f32_e32 v98, 1.0, v100
	v_and_b32_e32 v100, 0xffff0000, v149
	v_mul_f32_e32 v101, 0xbfb8aa3b, v100
	v_rcp_f32_e32 v98, v98
	v_exp_f32_e32 v101, v101
	v_mul_f32_e32 v97, v109, v97
	v_mul_f32_e32 v97, v156, v97
	v_mul_f32_e32 v98, v98, v99
	v_add_f32_e32 v99, 1.0, v101
	v_rcp_f32_e32 v99, v99
	v_mul_f32_e32 v98, v110, v98
	s_waitcnt vmcnt(0)
	v_mul_f32_e32 v96, v128, v96
	v_mul_f32_e32 v97, v129, v97
	v_mul_f32_e32 v99, v99, v100
	v_mul_f32_e32 v99, v111, v99
	v_mul_f32_e32 v98, v156, v98
	v_mul_f32_e32 v99, v156, v99
	v_mul_f32_e32 v98, v130, v98
	v_mul_f32_e32 v99, v131, v99
	v_cvt_pk_bf16_f32 v96, v96, v97
	v_cvt_pk_bf16_f32 v97, v98, v99
	v_permlane32_swap_b32_e32 v210, v212
	v_permlane32_swap_b32_e32 v211, v213
	v_permlane32_swap_b32_e32 v216, v218
	v_permlane32_swap_b32_e32 v217, v219
	v_permlane32_swap_b32_e32 v220, v222
	v_permlane32_swap_b32_e32 v221, v223
	v_permlane32_swap_b32_e32 v224, v226
	v_permlane32_swap_b32_e32 v225, v227
	v_mov_b64_e32 v[136:137], v[210:211]
	v_mov_b64_e32 v[138:139], v[212:213]
	v_mov_b64_e32 v[140:141], v[216:217]
	v_mov_b64_e32 v[142:143], v[218:219]
	v_mov_b64_e32 v[118:119], v[220:221]
	v_mov_b64_e32 v[116:117], v[222:223]
	v_mov_b64_e32 v[114:115], v[224:225]
	v_mov_b64_e32 v[112:113], v[226:227]
	ds_read_b128 v[188:191], v206 offset:256
	ds_read_b128 v[192:195], v206 offset:288
	ds_read_b128 v[196:199], v206 offset:320
	ds_read_b128 v[202:205], v206 offset:352
	v_lshlrev_b32_e32 v148, 16, v136
	v_mov_b64_e32 v[232:233], v[96:97]
	s_nop 1
	v_permlane32_swap_b32_e32 v230, v232
	v_permlane32_swap_b32_e32 v231, v233
	ds_write_b128 v206, v[230:233] offset:96
	global_load_dwordx4 v[120:123], v[146:147], off offset:256
	global_load_dwordx4 v[124:127], v[146:147], off offset:288
	global_load_dwordx4 v[128:131], v[146:147], off offset:320
	global_load_dwordx4 v[132:135], v[146:147], off offset:352
	global_load_dwordx4 v[108:111], v[146:147], off offset:384
	global_load_dwordx4 v[104:107], v[146:147], off offset:416
	v_mul_f32_e32 v96, 0xbfb8aa3b, v148
	v_exp_f32_e32 v149, v96
	v_and_b32_e32 v136, 0xffff0000, v136
	v_mul_f32_e32 v150, 0xbfb8aa3b, v136
	v_exp_f32_e32 v150, v150
	v_add_f32_e32 v149, 1.0, v149
	v_rcp_f32_e32 v149, v149
	global_load_dwordx4 v[100:103], v[146:147], off offset:448
	global_load_dwordx4 v[96:99], v[146:147], off offset:480
	v_mul_f32_e32 v148, v149, v148
	v_mul_f32_e32 v80, v80, v148
	v_add_f32_e32 v148, 1.0, v150
	v_rcp_f32_e32 v148, v148
	v_mul_f32_e32 v80, v156, v80
	v_lshlrev_b32_e32 v149, 16, v137
	v_mul_f32_e32 v150, 0xbfb8aa3b, v149
	v_exp_f32_e32 v150, v150
	s_waitcnt vmcnt(7)
	v_mul_f32_e32 v80, v120, v80
	v_mul_f32_e32 v120, v148, v136
	v_and_b32_e32 v136, 0xffff0000, v137
	v_mul_f32_e32 v137, 0xbfb8aa3b, v136
	v_exp_f32_e32 v137, v137
	v_mul_f32_e32 v81, v81, v120
	v_add_f32_e32 v120, 1.0, v150
	v_mul_f32_e32 v81, v156, v81
	v_rcp_f32_e32 v120, v120
	v_mul_f32_e32 v81, v121, v81
	v_add_f32_e32 v121, 1.0, v137
	v_rcp_f32_e32 v121, v121
	v_mul_f32_e32 v120, v120, v149
	v_mul_f32_e32 v82, v82, v120
	v_mul_f32_e32 v82, v156, v82
	v_mul_f32_e32 v120, v121, v136
	v_mul_f32_e32 v83, v83, v120
	v_lshlrev_b32_e32 v120, 16, v138
	v_mul_f32_e32 v121, 0xbfb8aa3b, v120
	v_exp_f32_e32 v121, v121
	v_mul_f32_e32 v83, v156, v83
	v_mul_f32_e32 v82, v122, v82
	v_mul_f32_e32 v83, v123, v83
	v_cvt_pk_bf16_f32 v80, v80, v81
	v_cvt_pk_bf16_f32 v81, v82, v83
	v_mov_b64_e32 v[238:239], v[80:81]
	v_add_f32_e32 v80, 1.0, v121
	v_and_b32_e32 v81, 0xffff0000, v138
	v_rcp_f32_e32 v80, v80
	v_mul_f32_e32 v82, 0xbfb8aa3b, v81
	v_exp_f32_e32 v82, v82
	v_lshlrev_b32_e32 v83, 16, v139
	v_mul_f32_e32 v80, v80, v120
	v_mul_f32_e32 v80, v84, v80
	v_add_f32_e32 v82, 1.0, v82
	v_mul_f32_e32 v84, 0xbfb8aa3b, v83
	v_rcp_f32_e32 v82, v82
	v_exp_f32_e32 v84, v84
	v_mul_f32_e32 v80, v156, v80
	s_waitcnt vmcnt(6)
	v_mul_f32_e32 v80, v124, v80
	v_mul_f32_e32 v81, v82, v81
	v_add_f32_e32 v82, 1.0, v84
	v_and_b32_e32 v84, 0xffff0000, v139
	v_mul_f32_e32 v81, v85, v81
	v_mul_f32_e32 v85, 0xbfb8aa3b, v84
	v_rcp_f32_e32 v82, v82
	v_exp_f32_e32 v85, v85
	v_mul_f32_e32 v81, v156, v81
	v_mul_f32_e32 v81, v125, v81
	v_mul_f32_e32 v82, v82, v83
	v_add_f32_e32 v83, 1.0, v85
	v_rcp_f32_e32 v83, v83
	v_mul_f32_e32 v82, v86, v82
	v_mul_f32_e32 v82, v156, v82
	v_mul_f32_e32 v82, v126, v82
	v_mul_f32_e32 v83, v83, v84
	v_lshlrev_b32_e32 v84, 16, v140
	v_mul_f32_e32 v85, 0xbfb8aa3b, v84
	v_mul_f32_e32 v83, v87, v83
	v_exp_f32_e32 v85, v85
	v_mul_f32_e32 v83, v156, v83
	v_mul_f32_e32 v83, v127, v83
	v_cvt_pk_bf16_f32 v80, v80, v81
	v_cvt_pk_bf16_f32 v81, v82, v83
	v_mov_b64_e32 v[240:241], v[80:81]
	s_nop 1
	v_permlane32_swap_b32_e32 v238, v240
	v_permlane32_swap_b32_e32 v239, v241
	ds_write_b128 v206, v[238:241] offset:128
	v_and_b32_e32 v81, 0xffff0000, v140
	v_add_f32_e32 v80, 1.0, v85
	v_mul_f32_e32 v82, 0xbfb8aa3b, v81
	v_rcp_f32_e32 v80, v80
	v_exp_f32_e32 v82, v82
	v_lshlrev_b32_e32 v83, 16, v141
	v_mul_f32_e32 v80, v80, v84
	v_add_f32_e32 v82, 1.0, v82
	v_mul_f32_e32 v84, 0xbfb8aa3b, v83
	v_rcp_f32_e32 v82, v82
	v_exp_f32_e32 v84, v84
	v_mul_f32_e32 v80, v88, v80
	v_mul_f32_e32 v80, v156, v80
	v_mul_f32_e32 v81, v82, v81
	v_add_f32_e32 v82, 1.0, v84
	v_and_b32_e32 v84, 0xffff0000, v141
	v_mul_f32_e32 v85, 0xbfb8aa3b, v84
	v_rcp_f32_e32 v82, v82
	v_exp_f32_e32 v85, v85
	v_mul_f32_e32 v81, v89, v81
	v_mul_f32_e32 v81, v156, v81
	v_mul_f32_e32 v82, v82, v83
	v_add_f32_e32 v83, 1.0, v85
	v_rcp_f32_e32 v83, v83
	v_mul_f32_e32 v82, v90, v82
	s_waitcnt vmcnt(5)
	v_mul_f32_e32 v80, v128, v80
	v_mul_f32_e32 v81, v129, v81
	v_mul_f32_e32 v83, v83, v84
	v_lshlrev_b32_e32 v84, 16, v142
	v_mul_f32_e32 v85, 0xbfb8aa3b, v84
	v_mul_f32_e32 v83, v91, v83
	v_exp_f32_e32 v85, v85
	v_mul_f32_e32 v82, v156, v82
	v_mul_f32_e32 v83, v156, v83
	v_mul_f32_e32 v82, v130, v82
	v_mul_f32_e32 v83, v131, v83
	v_cvt_pk_bf16_f32 v80, v80, v81
	v_cvt_pk_bf16_f32 v81, v82, v83
	v_mov_b64_e32 v[242:243], v[80:81]
	v_and_b32_e32 v81, 0xffff0000, v142
	v_add_f32_e32 v80, 1.0, v85
	v_mul_f32_e32 v82, 0xbfb8aa3b, v81
	v_rcp_f32_e32 v80, v80
	v_exp_f32_e32 v82, v82
	v_lshlrev_b32_e32 v83, 16, v143
	v_mul_f32_e32 v80, v80, v84
	v_add_f32_e32 v82, 1.0, v82
	v_mul_f32_e32 v84, 0xbfb8aa3b, v83
	v_rcp_f32_e32 v82, v82
	v_exp_f32_e32 v84, v84
	v_mul_f32_e32 v80, v92, v80
	v_mul_f32_e32 v80, v156, v80
	v_mul_f32_e32 v81, v82, v81
	v_add_f32_e32 v82, 1.0, v84
	v_and_b32_e32 v84, 0xffff0000, v143
	v_mul_f32_e32 v85, 0xbfb8aa3b, v84
	v_rcp_f32_e32 v82, v82
	v_exp_f32_e32 v85, v85
	v_mul_f32_e32 v81, v93, v81
	v_mul_f32_e32 v81, v156, v81
	v_mul_f32_e32 v82, v82, v83
	v_add_f32_e32 v83, 1.0, v85
	v_rcp_f32_e32 v83, v83
	v_mul_f32_e32 v82, v94, v82
	s_waitcnt vmcnt(4)
	v_mul_f32_e32 v80, v132, v80
	v_mul_f32_e32 v81, v133, v81
	v_mul_f32_e32 v83, v83, v84
	v_lshlrev_b32_e32 v84, 16, v118
	v_mul_f32_e32 v85, 0xbfb8aa3b, v84
	v_exp_f32_e32 v85, v85
	v_mul_f32_e32 v83, v95, v83
	v_mul_f32_e32 v82, v156, v82
	v_mul_f32_e32 v83, v156, v83
	v_mul_f32_e32 v82, v134, v82
	v_mul_f32_e32 v83, v135, v83
	v_cvt_pk_bf16_f32 v80, v80, v81
	v_cvt_pk_bf16_f32 v81, v82, v83
	v_mov_b64_e32 v[244:245], v[80:81]
	s_nop 1
	v_permlane32_swap_b32_e32 v242, v244
	v_permlane32_swap_b32_e32 v243, v245
	ds_write_b128 v206, v[242:245] offset:160
	v_add_f32_e32 v80, 1.0, v85
	v_and_b32_e32 v81, 0xffff0000, v118
	v_rcp_f32_e32 v80, v80
	v_mul_f32_e32 v82, 0xbfb8aa3b, v81
	v_exp_f32_e32 v82, v82
	v_mul_f32_e32 v80, v80, v84
	v_mul_f32_e32 v64, v64, v80
	v_add_f32_e32 v80, 1.0, v82
	v_lshlrev_b32_e32 v82, 16, v119
	v_rcp_f32_e32 v80, v80
	v_mul_f32_e32 v83, 0xbfb8aa3b, v82
	v_exp_f32_e32 v83, v83
	v_mul_f32_e32 v64, v156, v64
	v_mul_f32_e32 v80, v80, v81
	v_and_b32_e32 v81, 0xffff0000, v119
	v_mul_f32_e32 v65, v65, v80
	v_add_f32_e32 v80, 1.0, v83
	v_mul_f32_e32 v83, 0xbfb8aa3b, v81
	v_rcp_f32_e32 v80, v80
	v_exp_f32_e32 v83, v83
	v_mul_f32_e32 v65, v156, v65
	s_waitcnt vmcnt(3)
	v_mul_f32_e32 v64, v108, v64
	v_mul_f32_e32 v80, v80, v82
	v_add_f32_e32 v82, 1.0, v83
	v_rcp_f32_e32 v82, v82
	v_mul_f32_e32 v66, v66, v80
	v_mul_f32_e32 v65, v109, v65
	v_mul_f32_e32 v66, v156, v66
	v_mul_f32_e32 v80, v82, v81
	v_mul_f32_e32 v67, v67, v80
	v_lshlrev_b32_e32 v80, 16, v116
	v_mul_f32_e32 v81, 0xbfb8aa3b, v80
	v_exp_f32_e32 v81, v81
	v_mul_f32_e32 v67, v156, v67
	v_mul_f32_e32 v66, v110, v66
	v_mul_f32_e32 v67, v111, v67
	v_cvt_pk_bf16_f32 v64, v64, v65
	v_cvt_pk_bf16_f32 v65, v66, v67
	v_mov_b64_e32 v[246:247], v[64:65]
	v_add_f32_e32 v64, 1.0, v81
	v_and_b32_e32 v65, 0xffff0000, v116
	v_rcp_f32_e32 v64, v64
	v_mul_f32_e32 v66, 0xbfb8aa3b, v65
	v_exp_f32_e32 v66, v66
	v_lshlrev_b32_e32 v67, 16, v117
	v_mul_f32_e32 v64, v64, v80
	v_mul_f32_e32 v64, v68, v64
	v_add_f32_e32 v66, 1.0, v66
	v_mul_f32_e32 v68, 0xbfb8aa3b, v67
	v_rcp_f32_e32 v66, v66
	v_exp_f32_e32 v68, v68
	v_mul_f32_e32 v64, v156, v64
	s_waitcnt vmcnt(2)
	v_mul_f32_e32 v64, v104, v64
	v_mul_f32_e32 v65, v66, v65
	v_add_f32_e32 v66, 1.0, v68
	v_and_b32_e32 v68, 0xffff0000, v117
	v_mul_f32_e32 v65, v69, v65
	v_mul_f32_e32 v69, 0xbfb8aa3b, v68
	v_rcp_f32_e32 v66, v66
	v_exp_f32_e32 v69, v69
	v_mul_f32_e32 v65, v156, v65
	v_mul_f32_e32 v65, v105, v65
	v_mul_f32_e32 v66, v66, v67
	v_add_f32_e32 v67, 1.0, v69
	v_rcp_f32_e32 v67, v67
	v_mul_f32_e32 v66, v70, v66
	v_mul_f32_e32 v66, v156, v66
	v_mul_f32_e32 v66, v106, v66
	v_mul_f32_e32 v67, v67, v68
	v_lshlrev_b32_e32 v68, 16, v114
	v_mul_f32_e32 v69, 0xbfb8aa3b, v68
	v_mul_f32_e32 v67, v71, v67
	v_exp_f32_e32 v69, v69
	v_mul_f32_e32 v67, v156, v67
	v_mul_f32_e32 v67, v107, v67
	v_cvt_pk_bf16_f32 v64, v64, v65
	v_cvt_pk_bf16_f32 v65, v66, v67
	v_mov_b64_e32 v[248:249], v[64:65]
	s_nop 1
	v_permlane32_swap_b32_e32 v246, v248
	v_permlane32_swap_b32_e32 v247, v249
	ds_write_b128 v206, v[246:249] offset:192
	v_and_b32_e32 v65, 0xffff0000, v114
	v_add_f32_e32 v64, 1.0, v69
	v_mul_f32_e32 v66, 0xbfb8aa3b, v65
	v_rcp_f32_e32 v64, v64
	v_exp_f32_e32 v66, v66
	v_lshlrev_b32_e32 v67, 16, v115
	v_mul_f32_e32 v64, v64, v68
	v_add_f32_e32 v66, 1.0, v66
	v_mul_f32_e32 v68, 0xbfb8aa3b, v67
	v_rcp_f32_e32 v66, v66
	v_exp_f32_e32 v68, v68
	v_mul_f32_e32 v64, v72, v64
	v_mul_f32_e32 v64, v156, v64
	v_mul_f32_e32 v65, v66, v65
	v_add_f32_e32 v66, 1.0, v68
	v_and_b32_e32 v68, 0xffff0000, v115
	v_mul_f32_e32 v69, 0xbfb8aa3b, v68
	v_rcp_f32_e32 v66, v66
	v_exp_f32_e32 v69, v69
	v_mul_f32_e32 v65, v73, v65
	v_mul_f32_e32 v65, v156, v65
	v_mul_f32_e32 v66, v66, v67
	v_add_f32_e32 v67, 1.0, v69
	v_rcp_f32_e32 v67, v67
	v_mul_f32_e32 v66, v74, v66
	s_waitcnt vmcnt(1)
	v_mul_f32_e32 v64, v100, v64
	v_mul_f32_e32 v65, v101, v65
	v_mul_f32_e32 v67, v67, v68
	v_lshlrev_b32_e32 v68, 16, v112
	v_mul_f32_e32 v69, 0xbfb8aa3b, v68
	v_mul_f32_e32 v67, v75, v67
	v_exp_f32_e32 v69, v69
	v_mul_f32_e32 v66, v156, v66
	v_mul_f32_e32 v67, v156, v67
	v_mul_f32_e32 v66, v102, v66
	v_mul_f32_e32 v67, v103, v67
	v_cvt_pk_bf16_f32 v64, v64, v65
	v_cvt_pk_bf16_f32 v65, v66, v67
	v_mov_b64_e32 v[230:231], v[64:65]
	v_and_b32_e32 v65, 0xffff0000, v112
	v_add_f32_e32 v64, 1.0, v69
	v_mul_f32_e32 v66, 0xbfb8aa3b, v65
	v_rcp_f32_e32 v64, v64
	v_exp_f32_e32 v66, v66
	v_lshlrev_b32_e32 v67, 16, v113
	v_mul_f32_e32 v64, v64, v68
	v_add_f32_e32 v66, 1.0, v66
	v_mul_f32_e32 v68, 0xbfb8aa3b, v67
	v_rcp_f32_e32 v66, v66
	v_exp_f32_e32 v68, v68
	v_mul_f32_e32 v64, v76, v64
	v_mul_f32_e32 v64, v156, v64
	v_mul_f32_e32 v65, v66, v65
	v_add_f32_e32 v66, 1.0, v68
	v_and_b32_e32 v68, 0xffff0000, v113
	v_mul_f32_e32 v69, 0xbfb8aa3b, v68
	v_rcp_f32_e32 v66, v66
	v_exp_f32_e32 v69, v69
	v_mul_f32_e32 v65, v77, v65
	v_mul_f32_e32 v65, v156, v65
	v_mul_f32_e32 v66, v66, v67
	v_add_f32_e32 v67, 1.0, v69
	v_rcp_f32_e32 v67, v67
	v_mul_f32_e32 v66, v78, v66
	s_waitcnt vmcnt(0)
	v_mul_f32_e32 v64, v96, v64
	v_mul_f32_e32 v65, v97, v65
	v_mul_f32_e32 v67, v67, v68
	v_mul_f32_e32 v67, v79, v67
	v_mul_f32_e32 v66, v156, v66
	v_mul_f32_e32 v67, v156, v67
	v_mul_f32_e32 v66, v98, v66
	v_mul_f32_e32 v67, v99, v67
	v_cvt_pk_bf16_f32 v64, v64, v65
	v_cvt_pk_bf16_f32 v65, v66, v67
	s_waitcnt lgkmcnt(7)
	v_permlane32_swap_b32_e32 v188, v190
	v_permlane32_swap_b32_e32 v189, v191
	s_waitcnt lgkmcnt(6)
	v_permlane32_swap_b32_e32 v192, v194
	v_permlane32_swap_b32_e32 v193, v195
	s_waitcnt lgkmcnt(5)
	v_permlane32_swap_b32_e32 v196, v198
	v_permlane32_swap_b32_e32 v197, v199
	s_waitcnt lgkmcnt(4)
	v_permlane32_swap_b32_e32 v202, v204
	v_permlane32_swap_b32_e32 v203, v205
	v_mov_b64_e32 v[104:105], v[188:189]
	v_mov_b64_e32 v[106:107], v[190:191]
	v_mov_b64_e32 v[108:109], v[192:193]
	v_mov_b64_e32 v[110:111], v[194:195]
	v_mov_b64_e32 v[86:87], v[196:197]
	v_mov_b64_e32 v[84:85], v[198:199]
	v_mov_b64_e32 v[82:83], v[202:203]
	v_mov_b64_e32 v[80:81], v[204:205]
	ds_read_b128 v[210:213], v206 offset:384
	ds_read_b128 v[216:219], v206 offset:416
	ds_read_b128 v[220:223], v206 offset:448
	ds_read_b128 v[224:227], v206 offset:480
	v_lshlrev_b32_e32 v112, 16, v104
	v_mov_b64_e32 v[232:233], v[64:65]
	s_nop 1
	v_permlane32_swap_b32_e32 v230, v232
	v_permlane32_swap_b32_e32 v231, v233
	ds_write_b128 v206, v[230:233] offset:224
	global_load_dwordx4 v[88:91], v[146:147], off offset:512
	global_load_dwordx4 v[92:95], v[146:147], off offset:544
	global_load_dwordx4 v[96:99], v[146:147], off offset:576
	global_load_dwordx4 v[100:103], v[146:147], off offset:608
	global_load_dwordx4 v[76:79], v[146:147], off offset:640
	global_load_dwordx4 v[72:75], v[146:147], off offset:672
	v_mul_f32_e32 v64, 0xbfb8aa3b, v112
	v_exp_f32_e32 v113, v64
	v_and_b32_e32 v104, 0xffff0000, v104
	v_mul_f32_e32 v114, 0xbfb8aa3b, v104
	v_exp_f32_e32 v114, v114
	v_add_f32_e32 v113, 1.0, v113
	v_rcp_f32_e32 v113, v113
	global_load_dwordx4 v[68:71], v[146:147], off offset:704
	global_load_dwordx4 v[64:67], v[146:147], off offset:736
	v_mul_f32_e32 v112, v113, v112
	v_mul_f32_e32 v48, v48, v112
	v_add_f32_e32 v112, 1.0, v114
	v_rcp_f32_e32 v112, v112
	v_mul_f32_e32 v48, v156, v48
	v_lshlrev_b32_e32 v113, 16, v105
	v_mul_f32_e32 v114, 0xbfb8aa3b, v113
	v_exp_f32_e32 v114, v114
	s_waitcnt vmcnt(7)
	v_mul_f32_e32 v48, v88, v48
	v_mul_f32_e32 v88, v112, v104
	v_and_b32_e32 v104, 0xffff0000, v105
	v_mul_f32_e32 v105, 0xbfb8aa3b, v104
	v_exp_f32_e32 v105, v105
	v_mul_f32_e32 v49, v49, v88
	v_add_f32_e32 v88, 1.0, v114
	v_mul_f32_e32 v49, v156, v49
	v_rcp_f32_e32 v88, v88
	v_mul_f32_e32 v49, v89, v49
	v_add_f32_e32 v89, 1.0, v105
	v_rcp_f32_e32 v89, v89
	v_mul_f32_e32 v88, v88, v113
	v_mul_f32_e32 v50, v50, v88
	v_mul_f32_e32 v50, v156, v50
	v_mul_f32_e32 v88, v89, v104
	v_mul_f32_e32 v51, v51, v88
	v_lshlrev_b32_e32 v88, 16, v106
	v_mul_f32_e32 v89, 0xbfb8aa3b, v88
	v_exp_f32_e32 v89, v89
	v_mul_f32_e32 v51, v156, v51
	v_mul_f32_e32 v50, v90, v50
	v_mul_f32_e32 v51, v91, v51
	v_cvt_pk_bf16_f32 v48, v48, v49
	v_cvt_pk_bf16_f32 v49, v50, v51
	v_mov_b64_e32 v[238:239], v[48:49]
	v_add_f32_e32 v48, 1.0, v89
	v_and_b32_e32 v49, 0xffff0000, v106
	v_rcp_f32_e32 v48, v48
	v_mul_f32_e32 v50, 0xbfb8aa3b, v49
	v_exp_f32_e32 v50, v50
	v_lshlrev_b32_e32 v51, 16, v107
	v_mul_f32_e32 v48, v48, v88
	v_mul_f32_e32 v48, v52, v48
	v_add_f32_e32 v50, 1.0, v50
	v_mul_f32_e32 v52, 0xbfb8aa3b, v51
	v_rcp_f32_e32 v50, v50
	v_exp_f32_e32 v52, v52
	v_mul_f32_e32 v48, v156, v48
	s_waitcnt vmcnt(6)
	v_mul_f32_e32 v48, v92, v48
	v_mul_f32_e32 v49, v50, v49
	v_add_f32_e32 v50, 1.0, v52
	v_and_b32_e32 v52, 0xffff0000, v107
	v_mul_f32_e32 v49, v53, v49
	v_mul_f32_e32 v53, 0xbfb8aa3b, v52
	v_rcp_f32_e32 v50, v50
	v_exp_f32_e32 v53, v53
	v_mul_f32_e32 v49, v156, v49
	v_mul_f32_e32 v49, v93, v49
	v_mul_f32_e32 v50, v50, v51
	v_add_f32_e32 v51, 1.0, v53
	v_rcp_f32_e32 v51, v51
	v_mul_f32_e32 v50, v54, v50
	v_mul_f32_e32 v50, v156, v50
	v_mul_f32_e32 v50, v94, v50
	v_mul_f32_e32 v51, v51, v52
	v_lshlrev_b32_e32 v52, 16, v108
	v_mul_f32_e32 v53, 0xbfb8aa3b, v52
	v_mul_f32_e32 v51, v55, v51
	v_exp_f32_e32 v53, v53
	v_mul_f32_e32 v51, v156, v51
	v_mul_f32_e32 v51, v95, v51
	v_cvt_pk_bf16_f32 v48, v48, v49
	v_cvt_pk_bf16_f32 v49, v50, v51
	v_mov_b64_e32 v[240:241], v[48:49]
	s_nop 1
	v_permlane32_swap_b32_e32 v238, v240
	v_permlane32_swap_b32_e32 v239, v241
	ds_write_b128 v206, v[238:241] offset:256
	v_and_b32_e32 v49, 0xffff0000, v108
	v_add_f32_e32 v48, 1.0, v53
	v_mul_f32_e32 v50, 0xbfb8aa3b, v49
	v_rcp_f32_e32 v48, v48
	v_exp_f32_e32 v50, v50
	v_lshlrev_b32_e32 v51, 16, v109
	v_mul_f32_e32 v48, v48, v52
	v_add_f32_e32 v50, 1.0, v50
	v_mul_f32_e32 v52, 0xbfb8aa3b, v51
	v_rcp_f32_e32 v50, v50
	v_exp_f32_e32 v52, v52
	v_mul_f32_e32 v48, v56, v48
	v_mul_f32_e32 v48, v156, v48
	v_mul_f32_e32 v49, v50, v49
	v_add_f32_e32 v50, 1.0, v52
	v_and_b32_e32 v52, 0xffff0000, v109
	v_mul_f32_e32 v53, 0xbfb8aa3b, v52
	v_rcp_f32_e32 v50, v50
	v_exp_f32_e32 v53, v53
	v_mul_f32_e32 v49, v57, v49
	v_mul_f32_e32 v49, v156, v49
	v_mul_f32_e32 v50, v50, v51
	v_add_f32_e32 v51, 1.0, v53
	v_rcp_f32_e32 v51, v51
	v_mul_f32_e32 v50, v58, v50
	s_waitcnt vmcnt(5)
	v_mul_f32_e32 v48, v96, v48
	v_mul_f32_e32 v49, v97, v49
	v_mul_f32_e32 v51, v51, v52
	v_lshlrev_b32_e32 v52, 16, v110
	v_mul_f32_e32 v53, 0xbfb8aa3b, v52
	v_mul_f32_e32 v51, v59, v51
	v_exp_f32_e32 v53, v53
	v_mul_f32_e32 v50, v156, v50
	v_mul_f32_e32 v51, v156, v51
	v_mul_f32_e32 v50, v98, v50
	v_mul_f32_e32 v51, v99, v51
	v_cvt_pk_bf16_f32 v48, v48, v49
	v_cvt_pk_bf16_f32 v49, v50, v51
	v_mov_b64_e32 v[242:243], v[48:49]
	v_and_b32_e32 v49, 0xffff0000, v110
	v_add_f32_e32 v48, 1.0, v53
	v_mul_f32_e32 v50, 0xbfb8aa3b, v49
	v_rcp_f32_e32 v48, v48
	v_exp_f32_e32 v50, v50
	v_lshlrev_b32_e32 v51, 16, v111
	v_mul_f32_e32 v48, v48, v52
	v_add_f32_e32 v50, 1.0, v50
	v_mul_f32_e32 v52, 0xbfb8aa3b, v51
	v_rcp_f32_e32 v50, v50
	v_exp_f32_e32 v52, v52
	v_mul_f32_e32 v48, v60, v48
	v_mul_f32_e32 v48, v156, v48
	v_mul_f32_e32 v49, v50, v49
	v_add_f32_e32 v50, 1.0, v52
	v_and_b32_e32 v52, 0xffff0000, v111
	v_mul_f32_e32 v53, 0xbfb8aa3b, v52
	v_rcp_f32_e32 v50, v50
	v_exp_f32_e32 v53, v53
	v_mul_f32_e32 v49, v61, v49
	v_mul_f32_e32 v49, v156, v49
	v_mul_f32_e32 v50, v50, v51
	v_add_f32_e32 v51, 1.0, v53
	v_rcp_f32_e32 v51, v51
	v_mul_f32_e32 v50, v62, v50
	s_waitcnt vmcnt(4)
	v_mul_f32_e32 v48, v100, v48
	v_mul_f32_e32 v49, v101, v49
	v_mul_f32_e32 v51, v51, v52
	v_lshlrev_b32_e32 v52, 16, v86
	v_mul_f32_e32 v53, 0xbfb8aa3b, v52
	v_exp_f32_e32 v53, v53
	v_mul_f32_e32 v51, v63, v51
	v_mul_f32_e32 v50, v156, v50
	v_mul_f32_e32 v51, v156, v51
	v_mul_f32_e32 v50, v102, v50
	v_mul_f32_e32 v51, v103, v51
	v_cvt_pk_bf16_f32 v48, v48, v49
	v_cvt_pk_bf16_f32 v49, v50, v51
	v_mov_b64_e32 v[244:245], v[48:49]
	s_nop 1
	v_permlane32_swap_b32_e32 v242, v244
	v_permlane32_swap_b32_e32 v243, v245
	ds_write_b128 v206, v[242:245] offset:288
	v_add_f32_e32 v48, 1.0, v53
	v_and_b32_e32 v49, 0xffff0000, v86
	v_rcp_f32_e32 v48, v48
	v_mul_f32_e32 v50, 0xbfb8aa3b, v49
	v_exp_f32_e32 v50, v50
	v_mul_f32_e32 v48, v48, v52
	v_mul_f32_e32 v32, v32, v48
	v_add_f32_e32 v48, 1.0, v50
	v_lshlrev_b32_e32 v50, 16, v87
	v_rcp_f32_e32 v48, v48
	v_mul_f32_e32 v51, 0xbfb8aa3b, v50
	v_exp_f32_e32 v51, v51
	v_mul_f32_e32 v32, v156, v32
	v_mul_f32_e32 v48, v48, v49
	v_and_b32_e32 v49, 0xffff0000, v87
	v_mul_f32_e32 v33, v33, v48
	v_add_f32_e32 v48, 1.0, v51
	v_mul_f32_e32 v51, 0xbfb8aa3b, v49
	v_rcp_f32_e32 v48, v48
	v_exp_f32_e32 v51, v51
	v_mul_f32_e32 v33, v156, v33
	s_waitcnt vmcnt(3)
	v_mul_f32_e32 v32, v76, v32
	v_mul_f32_e32 v48, v48, v50
	v_add_f32_e32 v50, 1.0, v51
	v_rcp_f32_e32 v50, v50
	v_mul_f32_e32 v34, v34, v48
	v_mul_f32_e32 v33, v77, v33
	v_mul_f32_e32 v34, v156, v34
	v_mul_f32_e32 v48, v50, v49
	v_mul_f32_e32 v35, v35, v48
	v_lshlrev_b32_e32 v48, 16, v84
	v_mul_f32_e32 v49, 0xbfb8aa3b, v48
	v_exp_f32_e32 v49, v49
	v_mul_f32_e32 v35, v156, v35
	v_mul_f32_e32 v34, v78, v34
	v_mul_f32_e32 v35, v79, v35
	v_cvt_pk_bf16_f32 v32, v32, v33
	v_cvt_pk_bf16_f32 v33, v34, v35
	v_mov_b64_e32 v[246:247], v[32:33]
	v_add_f32_e32 v32, 1.0, v49
	v_and_b32_e32 v33, 0xffff0000, v84
	v_rcp_f32_e32 v32, v32
	v_mul_f32_e32 v34, 0xbfb8aa3b, v33
	v_exp_f32_e32 v34, v34
	v_lshlrev_b32_e32 v35, 16, v85
	v_mul_f32_e32 v32, v32, v48
	v_mul_f32_e32 v32, v36, v32
	v_add_f32_e32 v34, 1.0, v34
	v_mul_f32_e32 v36, 0xbfb8aa3b, v35
	v_rcp_f32_e32 v34, v34
	v_exp_f32_e32 v36, v36
	v_mul_f32_e32 v32, v156, v32
	s_waitcnt vmcnt(2)
	v_mul_f32_e32 v32, v72, v32
	v_mul_f32_e32 v33, v34, v33
	v_add_f32_e32 v34, 1.0, v36
	v_and_b32_e32 v36, 0xffff0000, v85
	v_mul_f32_e32 v33, v37, v33
	v_mul_f32_e32 v37, 0xbfb8aa3b, v36
	v_rcp_f32_e32 v34, v34
	v_exp_f32_e32 v37, v37
	v_mul_f32_e32 v33, v156, v33
	v_mul_f32_e32 v33, v73, v33
	v_mul_f32_e32 v34, v34, v35
	v_add_f32_e32 v35, 1.0, v37
	v_rcp_f32_e32 v35, v35
	v_mul_f32_e32 v34, v38, v34
	v_mul_f32_e32 v34, v156, v34
	v_mul_f32_e32 v34, v74, v34
	v_mul_f32_e32 v35, v35, v36
	v_lshlrev_b32_e32 v36, 16, v82
	v_mul_f32_e32 v37, 0xbfb8aa3b, v36
	v_mul_f32_e32 v35, v39, v35
	v_exp_f32_e32 v37, v37
	v_mul_f32_e32 v35, v156, v35
	v_mul_f32_e32 v35, v75, v35
	v_cvt_pk_bf16_f32 v32, v32, v33
	v_cvt_pk_bf16_f32 v33, v34, v35
	v_mov_b64_e32 v[248:249], v[32:33]
	s_nop 1
	v_permlane32_swap_b32_e32 v246, v248
	v_permlane32_swap_b32_e32 v247, v249
	ds_write_b128 v206, v[246:249] offset:320
	v_and_b32_e32 v33, 0xffff0000, v82
	v_add_f32_e32 v32, 1.0, v37
	v_mul_f32_e32 v34, 0xbfb8aa3b, v33
	v_rcp_f32_e32 v32, v32
	v_exp_f32_e32 v34, v34
	v_lshlrev_b32_e32 v35, 16, v83
	v_mul_f32_e32 v32, v32, v36
	v_add_f32_e32 v34, 1.0, v34
	v_mul_f32_e32 v36, 0xbfb8aa3b, v35
	v_rcp_f32_e32 v34, v34
	v_exp_f32_e32 v36, v36
	v_mul_f32_e32 v32, v40, v32
	v_mul_f32_e32 v32, v156, v32
	v_mul_f32_e32 v33, v34, v33
	v_add_f32_e32 v34, 1.0, v36
	v_and_b32_e32 v36, 0xffff0000, v83
	v_mul_f32_e32 v37, 0xbfb8aa3b, v36
	v_rcp_f32_e32 v34, v34
	v_exp_f32_e32 v37, v37
	v_mul_f32_e32 v33, v41, v33
	v_mul_f32_e32 v33, v156, v33
	v_mul_f32_e32 v34, v34, v35
	v_add_f32_e32 v35, 1.0, v37
	v_rcp_f32_e32 v35, v35
	v_mul_f32_e32 v34, v42, v34
	s_waitcnt vmcnt(1)
	v_mul_f32_e32 v32, v68, v32
	v_mul_f32_e32 v33, v69, v33
	v_mul_f32_e32 v35, v35, v36
	v_lshlrev_b32_e32 v36, 16, v80
	v_mul_f32_e32 v37, 0xbfb8aa3b, v36
	v_mul_f32_e32 v35, v43, v35
	v_exp_f32_e32 v37, v37
	v_mul_f32_e32 v34, v156, v34
	v_mul_f32_e32 v35, v156, v35
	v_mul_f32_e32 v34, v70, v34
	v_mul_f32_e32 v35, v71, v35
	v_cvt_pk_bf16_f32 v32, v32, v33
	v_cvt_pk_bf16_f32 v33, v34, v35
	v_mov_b64_e32 v[230:231], v[32:33]
	v_and_b32_e32 v33, 0xffff0000, v80
	v_add_f32_e32 v32, 1.0, v37
	v_mul_f32_e32 v34, 0xbfb8aa3b, v33
	v_rcp_f32_e32 v32, v32
	v_exp_f32_e32 v34, v34
	v_lshlrev_b32_e32 v35, 16, v81
	v_mul_f32_e32 v32, v32, v36
	v_add_f32_e32 v34, 1.0, v34
	v_mul_f32_e32 v36, 0xbfb8aa3b, v35
	v_rcp_f32_e32 v34, v34
	v_exp_f32_e32 v36, v36
	v_mul_f32_e32 v32, v44, v32
	v_mul_f32_e32 v32, v156, v32
	v_mul_f32_e32 v33, v34, v33
	v_add_f32_e32 v34, 1.0, v36
	v_and_b32_e32 v36, 0xffff0000, v81
	v_mul_f32_e32 v37, 0xbfb8aa3b, v36
	v_rcp_f32_e32 v34, v34
	v_exp_f32_e32 v37, v37
	v_mul_f32_e32 v33, v45, v33
	v_mul_f32_e32 v33, v156, v33
	v_mul_f32_e32 v34, v34, v35
	v_add_f32_e32 v35, 1.0, v37
	v_rcp_f32_e32 v35, v35
	v_mul_f32_e32 v34, v46, v34
	s_waitcnt vmcnt(0)
	v_mul_f32_e32 v32, v64, v32
	v_mul_f32_e32 v33, v65, v33
	v_mul_f32_e32 v35, v35, v36
	v_mul_f32_e32 v35, v47, v35
	v_mul_f32_e32 v34, v156, v34
	v_mul_f32_e32 v35, v156, v35
	v_mul_f32_e32 v34, v66, v34
	v_mul_f32_e32 v35, v67, v35
	v_cvt_pk_bf16_f32 v32, v32, v33
	v_cvt_pk_bf16_f32 v33, v34, v35
	s_waitcnt lgkmcnt(7)
	v_permlane32_swap_b32_e32 v210, v212
	v_permlane32_swap_b32_e32 v211, v213
	s_waitcnt lgkmcnt(6)
	v_permlane32_swap_b32_e32 v216, v218
	v_permlane32_swap_b32_e32 v217, v219
	s_waitcnt lgkmcnt(5)
	v_permlane32_swap_b32_e32 v220, v222
	v_permlane32_swap_b32_e32 v221, v223
	s_waitcnt lgkmcnt(4)
	v_permlane32_swap_b32_e32 v224, v226
	v_permlane32_swap_b32_e32 v225, v227
	v_mov_b64_e32 v[72:73], v[210:211]
	v_mov_b64_e32 v[74:75], v[212:213]
	v_mov_b64_e32 v[76:77], v[216:217]
	v_mov_b64_e32 v[78:79], v[218:219]
	v_mov_b64_e32 v[54:55], v[220:221]
	v_mov_b64_e32 v[52:53], v[222:223]
	v_mov_b64_e32 v[50:51], v[224:225]
	v_mov_b64_e32 v[48:49], v[226:227]
	v_lshlrev_b32_e32 v80, 16, v72
	v_mov_b64_e32 v[232:233], v[32:33]
	s_nop 1
	v_permlane32_swap_b32_e32 v230, v232
	v_permlane32_swap_b32_e32 v231, v233
	ds_write_b128 v206, v[230:233] offset:352
	global_load_dwordx4 v[56:59], v[146:147], off offset:768
	global_load_dwordx4 v[60:63], v[146:147], off offset:800
	global_load_dwordx4 v[64:67], v[146:147], off offset:832
	global_load_dwordx4 v[68:71], v[146:147], off offset:864
	global_load_dwordx4 v[44:47], v[146:147], off offset:896
	global_load_dwordx4 v[40:43], v[146:147], off offset:928
	v_mul_f32_e32 v32, 0xbfb8aa3b, v80
	v_exp_f32_e32 v81, v32
	v_and_b32_e32 v72, 0xffff0000, v72
	v_mul_f32_e32 v82, 0xbfb8aa3b, v72
	v_exp_f32_e32 v82, v82
	v_add_f32_e32 v81, 1.0, v81
	v_rcp_f32_e32 v81, v81
	global_load_dwordx4 v[36:39], v[146:147], off offset:960
	global_load_dwordx4 v[32:35], v[146:147], off offset:992
	v_mul_f32_e32 v80, v81, v80
	v_mul_f32_e32 v16, v16, v80
	v_add_f32_e32 v80, 1.0, v82
	v_rcp_f32_e32 v80, v80
	v_mul_f32_e32 v16, v156, v16
	v_lshlrev_b32_e32 v81, 16, v73
	v_mul_f32_e32 v82, 0xbfb8aa3b, v81
	v_exp_f32_e32 v82, v82
	s_waitcnt vmcnt(7)
	v_mul_f32_e32 v16, v56, v16
	v_mul_f32_e32 v56, v80, v72
	v_and_b32_e32 v72, 0xffff0000, v73
	v_mul_f32_e32 v73, 0xbfb8aa3b, v72
	v_exp_f32_e32 v73, v73
	v_mul_f32_e32 v17, v17, v56
	v_add_f32_e32 v56, 1.0, v82
	v_mul_f32_e32 v17, v156, v17
	v_rcp_f32_e32 v56, v56
	v_mul_f32_e32 v17, v57, v17
	v_add_f32_e32 v57, 1.0, v73
	v_rcp_f32_e32 v57, v57
	v_mul_f32_e32 v56, v56, v81
	v_mul_f32_e32 v18, v18, v56
	v_mul_f32_e32 v18, v156, v18
	v_mul_f32_e32 v56, v57, v72
	v_mul_f32_e32 v19, v19, v56
	v_lshlrev_b32_e32 v56, 16, v74
	v_mul_f32_e32 v57, 0xbfb8aa3b, v56
	v_exp_f32_e32 v57, v57
	v_mul_f32_e32 v19, v156, v19
	v_mul_f32_e32 v18, v58, v18
	v_mul_f32_e32 v19, v59, v19
	v_cvt_pk_bf16_f32 v16, v16, v17
	v_cvt_pk_bf16_f32 v17, v18, v19
	v_mov_b64_e32 v[238:239], v[16:17]
	v_add_f32_e32 v16, 1.0, v57
	v_and_b32_e32 v17, 0xffff0000, v74
	v_rcp_f32_e32 v16, v16
	v_mul_f32_e32 v18, 0xbfb8aa3b, v17
	v_exp_f32_e32 v18, v18
	v_lshlrev_b32_e32 v19, 16, v75
	v_mul_f32_e32 v16, v16, v56
	v_mul_f32_e32 v16, v20, v16
	v_add_f32_e32 v18, 1.0, v18
	v_mul_f32_e32 v20, 0xbfb8aa3b, v19
	v_rcp_f32_e32 v18, v18
	v_exp_f32_e32 v20, v20
	v_mul_f32_e32 v16, v156, v16
	s_waitcnt vmcnt(6)
	v_mul_f32_e32 v16, v60, v16
	v_mul_f32_e32 v17, v18, v17
	v_add_f32_e32 v18, 1.0, v20
	v_and_b32_e32 v20, 0xffff0000, v75
	v_mul_f32_e32 v17, v21, v17
	v_mul_f32_e32 v21, 0xbfb8aa3b, v20
	v_rcp_f32_e32 v18, v18
	v_exp_f32_e32 v21, v21
	v_mul_f32_e32 v17, v156, v17
	v_mul_f32_e32 v17, v61, v17
	v_mul_f32_e32 v18, v18, v19
	v_add_f32_e32 v19, 1.0, v21
	v_rcp_f32_e32 v19, v19
	v_mul_f32_e32 v18, v22, v18
	v_mul_f32_e32 v18, v156, v18
	v_mul_f32_e32 v18, v62, v18
	v_mul_f32_e32 v19, v19, v20
	v_lshlrev_b32_e32 v20, 16, v76
	v_mul_f32_e32 v21, 0xbfb8aa3b, v20
	v_mul_f32_e32 v19, v23, v19
	v_exp_f32_e32 v21, v21
	v_mul_f32_e32 v19, v156, v19
	v_mul_f32_e32 v19, v63, v19
	v_cvt_pk_bf16_f32 v16, v16, v17
	v_cvt_pk_bf16_f32 v17, v18, v19
	v_mov_b64_e32 v[240:241], v[16:17]
	s_nop 1
	v_permlane32_swap_b32_e32 v238, v240
	v_permlane32_swap_b32_e32 v239, v241
	ds_write_b128 v206, v[238:241] offset:384
	v_and_b32_e32 v17, 0xffff0000, v76
	v_add_f32_e32 v16, 1.0, v21
	v_mul_f32_e32 v18, 0xbfb8aa3b, v17
	v_rcp_f32_e32 v16, v16
	v_exp_f32_e32 v18, v18
	v_lshlrev_b32_e32 v19, 16, v77
	v_mul_f32_e32 v16, v16, v20
	v_add_f32_e32 v18, 1.0, v18
	v_mul_f32_e32 v20, 0xbfb8aa3b, v19
	v_rcp_f32_e32 v18, v18
	v_exp_f32_e32 v20, v20
	v_mul_f32_e32 v16, v24, v16
	v_mul_f32_e32 v16, v156, v16
	v_mul_f32_e32 v17, v18, v17
	v_add_f32_e32 v18, 1.0, v20
	v_and_b32_e32 v20, 0xffff0000, v77
	v_mul_f32_e32 v21, 0xbfb8aa3b, v20
	v_rcp_f32_e32 v18, v18
	v_exp_f32_e32 v21, v21
	v_mul_f32_e32 v17, v25, v17
	v_mul_f32_e32 v17, v156, v17
	v_mul_f32_e32 v18, v18, v19
	v_add_f32_e32 v19, 1.0, v21
	v_rcp_f32_e32 v19, v19
	v_mul_f32_e32 v18, v26, v18
	s_waitcnt vmcnt(5)
	v_mul_f32_e32 v16, v64, v16
	v_mul_f32_e32 v17, v65, v17
	v_mul_f32_e32 v19, v19, v20
	v_lshlrev_b32_e32 v20, 16, v78
	v_mul_f32_e32 v21, 0xbfb8aa3b, v20
	v_mul_f32_e32 v19, v27, v19
	v_exp_f32_e32 v21, v21
	v_mul_f32_e32 v18, v156, v18
	v_mul_f32_e32 v19, v156, v19
	v_mul_f32_e32 v18, v66, v18
	v_mul_f32_e32 v19, v67, v19
	v_cvt_pk_bf16_f32 v16, v16, v17
	v_cvt_pk_bf16_f32 v17, v18, v19
	v_mov_b64_e32 v[242:243], v[16:17]
	v_and_b32_e32 v17, 0xffff0000, v78
	v_add_f32_e32 v16, 1.0, v21
	v_mul_f32_e32 v18, 0xbfb8aa3b, v17
	v_rcp_f32_e32 v16, v16
	v_exp_f32_e32 v18, v18
	v_lshlrev_b32_e32 v19, 16, v79
	v_mul_f32_e32 v16, v16, v20
	v_add_f32_e32 v18, 1.0, v18
	v_mul_f32_e32 v20, 0xbfb8aa3b, v19
	v_rcp_f32_e32 v18, v18
	v_exp_f32_e32 v20, v20
	v_mul_f32_e32 v16, v28, v16
	v_mul_f32_e32 v16, v156, v16
	v_mul_f32_e32 v17, v18, v17
	v_add_f32_e32 v18, 1.0, v20
	v_and_b32_e32 v20, 0xffff0000, v79
	v_mul_f32_e32 v21, 0xbfb8aa3b, v20
	v_rcp_f32_e32 v18, v18
	v_exp_f32_e32 v21, v21
	v_mul_f32_e32 v17, v29, v17
	v_mul_f32_e32 v17, v156, v17
	v_mul_f32_e32 v18, v18, v19
	v_add_f32_e32 v19, 1.0, v21
	v_rcp_f32_e32 v19, v19
	v_mul_f32_e32 v18, v30, v18
	s_waitcnt vmcnt(4)
	v_mul_f32_e32 v16, v68, v16
	v_mul_f32_e32 v17, v69, v17
	v_mul_f32_e32 v19, v19, v20
	v_lshlrev_b32_e32 v20, 16, v54
	v_mul_f32_e32 v21, 0xbfb8aa3b, v20
	v_exp_f32_e32 v21, v21
	v_mul_f32_e32 v19, v31, v19
	v_mul_f32_e32 v18, v156, v18
	v_mul_f32_e32 v19, v156, v19
	v_mul_f32_e32 v18, v70, v18
	v_mul_f32_e32 v19, v71, v19
	v_cvt_pk_bf16_f32 v16, v16, v17
	v_cvt_pk_bf16_f32 v17, v18, v19
	v_mov_b64_e32 v[244:245], v[16:17]
	s_nop 1
	v_permlane32_swap_b32_e32 v242, v244
	v_permlane32_swap_b32_e32 v243, v245
	ds_write_b128 v206, v[242:245] offset:416
	v_add_f32_e32 v16, 1.0, v21
	v_and_b32_e32 v17, 0xffff0000, v54
	v_rcp_f32_e32 v16, v16
	v_mul_f32_e32 v18, 0xbfb8aa3b, v17
	v_exp_f32_e32 v18, v18
	v_mul_f32_e32 v16, v16, v20
	v_mul_f32_e32 v0, v0, v16
	v_add_f32_e32 v16, 1.0, v18
	v_lshlrev_b32_e32 v18, 16, v55
	v_rcp_f32_e32 v16, v16
	v_mul_f32_e32 v19, 0xbfb8aa3b, v18
	v_exp_f32_e32 v19, v19
	v_mul_f32_e32 v0, v156, v0
	v_mul_f32_e32 v16, v16, v17
	v_and_b32_e32 v17, 0xffff0000, v55
	v_mul_f32_e32 v1, v1, v16
	v_add_f32_e32 v16, 1.0, v19
	v_mul_f32_e32 v19, 0xbfb8aa3b, v17
	v_rcp_f32_e32 v16, v16
	v_exp_f32_e32 v19, v19
	v_mul_f32_e32 v1, v156, v1
	s_waitcnt vmcnt(3)
	v_mul_f32_e32 v0, v44, v0
	v_mul_f32_e32 v16, v16, v18
	v_add_f32_e32 v18, 1.0, v19
	v_rcp_f32_e32 v18, v18
	v_mul_f32_e32 v2, v2, v16
	v_mul_f32_e32 v1, v45, v1
	v_mul_f32_e32 v2, v156, v2
	v_mul_f32_e32 v16, v18, v17
	v_mul_f32_e32 v3, v3, v16
	v_lshlrev_b32_e32 v16, 16, v52
	v_mul_f32_e32 v17, 0xbfb8aa3b, v16
	v_exp_f32_e32 v17, v17
	v_mul_f32_e32 v3, v156, v3
	v_mul_f32_e32 v2, v46, v2
	v_mul_f32_e32 v3, v47, v3
	v_cvt_pk_bf16_f32 v0, v0, v1
	v_cvt_pk_bf16_f32 v1, v2, v3
	v_mov_b64_e32 v[246:247], v[0:1]
	v_add_f32_e32 v0, 1.0, v17
	v_and_b32_e32 v1, 0xffff0000, v52
	v_rcp_f32_e32 v0, v0
	v_mul_f32_e32 v2, 0xbfb8aa3b, v1
	v_exp_f32_e32 v2, v2
	v_lshlrev_b32_e32 v3, 16, v53
	v_mul_f32_e32 v0, v0, v16
	v_mul_f32_e32 v0, v4, v0
	v_add_f32_e32 v2, 1.0, v2
	v_mul_f32_e32 v4, 0xbfb8aa3b, v3
	v_rcp_f32_e32 v2, v2
	v_exp_f32_e32 v4, v4
	v_mul_f32_e32 v0, v156, v0
	s_waitcnt vmcnt(2)
	v_mul_f32_e32 v0, v40, v0
	v_mul_f32_e32 v1, v2, v1
	v_add_f32_e32 v2, 1.0, v4
	v_and_b32_e32 v4, 0xffff0000, v53
	v_mul_f32_e32 v1, v5, v1
	v_mul_f32_e32 v5, 0xbfb8aa3b, v4
	v_rcp_f32_e32 v2, v2
	v_exp_f32_e32 v5, v5
	v_mul_f32_e32 v1, v156, v1
	v_mul_f32_e32 v1, v41, v1
	v_mul_f32_e32 v2, v2, v3
	v_add_f32_e32 v3, 1.0, v5
	v_rcp_f32_e32 v3, v3
	v_mul_f32_e32 v2, v6, v2
	v_mul_f32_e32 v2, v156, v2
	v_mul_f32_e32 v2, v42, v2
	v_mul_f32_e32 v3, v3, v4
	v_lshlrev_b32_e32 v4, 16, v50
	v_mul_f32_e32 v5, 0xbfb8aa3b, v4
	v_mul_f32_e32 v3, v7, v3
	v_exp_f32_e32 v5, v5
	v_mul_f32_e32 v3, v156, v3
	v_mul_f32_e32 v3, v43, v3
	v_cvt_pk_bf16_f32 v0, v0, v1
	v_cvt_pk_bf16_f32 v1, v2, v3
	v_mov_b64_e32 v[248:249], v[0:1]
	s_nop 1
	v_permlane32_swap_b32_e32 v246, v248
	v_permlane32_swap_b32_e32 v247, v249
	ds_write_b128 v206, v[246:249] offset:448
	v_and_b32_e32 v1, 0xffff0000, v50
	v_add_f32_e32 v0, 1.0, v5
	v_mul_f32_e32 v2, 0xbfb8aa3b, v1
	v_rcp_f32_e32 v0, v0
	v_exp_f32_e32 v2, v2
	v_lshlrev_b32_e32 v3, 16, v51
	v_mul_f32_e32 v0, v0, v4
	v_add_f32_e32 v2, 1.0, v2
	v_mul_f32_e32 v4, 0xbfb8aa3b, v3
	v_rcp_f32_e32 v2, v2
	v_exp_f32_e32 v4, v4
	v_mul_f32_e32 v0, v8, v0
	v_mul_f32_e32 v0, v156, v0
	v_mul_f32_e32 v1, v2, v1
	v_add_f32_e32 v2, 1.0, v4
	v_and_b32_e32 v4, 0xffff0000, v51
	v_mul_f32_e32 v5, 0xbfb8aa3b, v4
	v_rcp_f32_e32 v2, v2
	v_exp_f32_e32 v5, v5
	v_mul_f32_e32 v1, v9, v1
	v_mul_f32_e32 v1, v156, v1
	v_mul_f32_e32 v2, v2, v3
	v_add_f32_e32 v3, 1.0, v5
	v_rcp_f32_e32 v3, v3
	v_mul_f32_e32 v2, v10, v2
	s_waitcnt vmcnt(1)
	v_mul_f32_e32 v0, v36, v0
	v_mul_f32_e32 v1, v37, v1
	v_mul_f32_e32 v3, v3, v4
	v_lshlrev_b32_e32 v4, 16, v48
	v_mul_f32_e32 v5, 0xbfb8aa3b, v4
	v_mul_f32_e32 v3, v11, v3
	v_exp_f32_e32 v5, v5
	v_mul_f32_e32 v2, v156, v2
	v_mul_f32_e32 v3, v156, v3
	v_mul_f32_e32 v2, v38, v2
	v_mul_f32_e32 v3, v39, v3
	v_cvt_pk_bf16_f32 v0, v0, v1
	v_cvt_pk_bf16_f32 v1, v2, v3
	v_mov_b64_e32 v[230:231], v[0:1]
	v_and_b32_e32 v1, 0xffff0000, v48
	v_add_f32_e32 v0, 1.0, v5
	v_mul_f32_e32 v2, 0xbfb8aa3b, v1
	v_rcp_f32_e32 v0, v0
	v_exp_f32_e32 v2, v2
	v_lshlrev_b32_e32 v3, 16, v49
	v_mul_f32_e32 v0, v0, v4
	v_add_f32_e32 v2, 1.0, v2
	v_mul_f32_e32 v4, 0xbfb8aa3b, v3
	v_rcp_f32_e32 v2, v2
	v_exp_f32_e32 v4, v4
	v_mul_f32_e32 v0, v12, v0
	v_mul_f32_e32 v0, v156, v0
	v_mul_f32_e32 v1, v2, v1
	v_add_f32_e32 v2, 1.0, v4
	v_and_b32_e32 v4, 0xffff0000, v49
	v_mul_f32_e32 v5, 0xbfb8aa3b, v4
	v_rcp_f32_e32 v2, v2
	v_exp_f32_e32 v5, v5
	v_mul_f32_e32 v1, v13, v1
	v_mul_f32_e32 v1, v156, v1
	v_mul_f32_e32 v2, v2, v3
	v_add_f32_e32 v3, 1.0, v5
	v_rcp_f32_e32 v3, v3
	v_mul_f32_e32 v2, v14, v2
	s_waitcnt vmcnt(0)
	v_mul_f32_e32 v0, v32, v0
	v_mul_f32_e32 v1, v33, v1
	v_mul_f32_e32 v3, v3, v4
	v_mul_f32_e32 v3, v15, v3
	v_mul_f32_e32 v2, v156, v2
	v_mul_f32_e32 v3, v156, v3
	v_mul_f32_e32 v2, v34, v2
	v_mul_f32_e32 v3, v35, v3
	v_cvt_pk_bf16_f32 v0, v0, v1
	v_cvt_pk_bf16_f32 v1, v2, v3
	v_mov_b64_e32 v[232:233], v[0:1]
	s_nop 1
	v_permlane32_swap_b32_e32 v230, v232
	v_permlane32_swap_b32_e32 v231, v233
	ds_write_b128 v206, v[230:233] offset:480
	ds_read_b128 v[96:99], v207
	ds_read_b128 v[100:103], v207 offset:1056
	ds_read_b128 v[104:107], v207 offset:2112
	ds_read_b128 v[108:111], v207 offset:3168
	ds_read_b128 v[112:115], v207 offset:4224
	ds_read_b128 v[116:119], v207 offset:5280
	ds_read_b128 v[120:123], v207 offset:6336
	s_waitcnt lgkmcnt(8)
	ds_read_b128 v[124:127], v207 offset:7392
	ds_read_b128 v[148:151], v207 offset:8448
	ds_read_b128 v[152:155], v207 offset:9504
	ds_read_b128 v[156:159], v207 offset:10560
	ds_read_b128 v[160:163], v207 offset:11616
	ds_read_b128 v[164:167], v207 offset:12672
	ds_read_b128 v[168:171], v207 offset:13728
	ds_read_b128 v[172:175], v207 offset:14784
	s_waitcnt lgkmcnt(8)
	ds_read_b128 v[176:179], v207 offset:15840
	v_mov_b64_e32 v[180:181], v[184:185]
	global_store_dwordx4 v[180:181], v[96:99], off
	v_lshl_add_u64 v[180:181], v[180:181], 0, s[84:85]
	global_store_dwordx4 v[180:181], v[100:103], off
	v_lshl_add_u64 v[180:181], v[180:181], 0, s[84:85]
	global_store_dwordx4 v[180:181], v[104:107], off
	v_lshl_add_u64 v[180:181], v[180:181], 0, s[84:85]
	global_store_dwordx4 v[180:181], v[108:111], off
	v_lshl_add_u64 v[180:181], v[180:181], 0, s[84:85]
	global_store_dwordx4 v[180:181], v[112:115], off
	v_lshl_add_u64 v[180:181], v[180:181], 0, s[84:85]
	global_store_dwordx4 v[180:181], v[116:119], off
	v_lshl_add_u64 v[180:181], v[180:181], 0, s[84:85]
	global_store_dwordx4 v[180:181], v[120:123], off
	v_lshl_add_u64 v[180:181], v[180:181], 0, s[84:85]
	s_waitcnt lgkmcnt(8)
	global_store_dwordx4 v[180:181], v[124:127], off
	v_lshl_add_u64 v[180:181], v[180:181], 0, s[84:85]
	s_waitcnt lgkmcnt(7)
	global_store_dwordx4 v[180:181], v[148:151], off
	v_lshl_add_u64 v[180:181], v[180:181], 0, s[84:85]
	s_waitcnt lgkmcnt(6)
	global_store_dwordx4 v[180:181], v[152:155], off
	v_lshl_add_u64 v[180:181], v[180:181], 0, s[84:85]
	s_waitcnt lgkmcnt(5)
	global_store_dwordx4 v[180:181], v[156:159], off
	v_lshl_add_u64 v[180:181], v[180:181], 0, s[84:85]
	s_waitcnt lgkmcnt(4)
	global_store_dwordx4 v[180:181], v[160:163], off
	v_lshl_add_u64 v[180:181], v[180:181], 0, s[84:85]
	s_waitcnt lgkmcnt(3)
	global_store_dwordx4 v[180:181], v[164:167], off
	v_lshl_add_u64 v[180:181], v[180:181], 0, s[84:85]
	s_waitcnt lgkmcnt(2)
	global_store_dwordx4 v[180:181], v[168:171], off
	v_lshl_add_u64 v[180:181], v[180:181], 0, s[84:85]
	s_waitcnt lgkmcnt(1)
	global_store_dwordx4 v[180:181], v[172:175], off
	v_lshl_add_u64 v[180:181], v[180:181], 0, s[84:85]
	s_waitcnt lgkmcnt(0)
	global_store_dwordx4 v[180:181], v[176:179], off
	s_cbranch_scc1 .LBB0_567

.LBB0_686:
	v_lshl_add_u32 v128, s37, 8, v209
	v_ashrrev_i32_e32 v129, 31, v128
	v_lshlrev_b64 v[128:129], 12, v[128:129]
	v_lshl_add_u64 v[128:129], s[4:5], 0, v[128:129]
	s_lshl_b32 s96, s36, 9
	v_lshl_add_u64 v[128:129], v[128:129], 0, s[96:97]
	v_readfirstlane_b32 s82, v209
	v_and_b32_e32 v180, 31, v209
	v_lshrrev_b32_e32 v181, 2, v208
	v_sub_u32_e32 v182, v181, v180
	v_ashrrev_i32_e32 v183, 31, v182
	s_mul_i32 s82, s82, 0x210
	s_mov_b64 s[84:85], 0x2000
	v_lshlrev_b64 v[182:183], 12, v[182:183]
	v_lshl_add_u64 v[184:185], v[128:129], 0, v[182:183]
	v_lshlrev_b32_e32 v182, 4, v180
	v_mov_b32_e32 v183, 0
	v_lshl_add_u64 v[184:185], v[184:185], 0, v[182:183]
	v_mul_u32_u24_e32 v206, 0x210, v180
	v_lshl_add_u32 v206, v181, 4, v206
	v_add_u32_e32 v206, s82, v206
	v_mul_u32_u24_e32 v207, 0x210, v181
	v_lshl_add_u32 v207, v180, 4, v207
	v_add_u32_e32 v207, s82, v207
	v_mov_b64_e32 v[178:179], v[184:185]
	global_load_dwordx4 v[188:191], v[178:179], off
	v_lshl_add_u64 v[178:179], v[178:179], 0, s[84:85]
	global_load_dwordx4 v[192:195], v[178:179], off
	v_lshl_add_u64 v[178:179], v[178:179], 0, s[84:85]
	global_load_dwordx4 v[196:199], v[178:179], off
	v_lshl_add_u64 v[178:179], v[178:179], 0, s[84:85]
	global_load_dwordx4 v[202:205], v[178:179], off
	v_lshl_add_u64 v[178:179], v[178:179], 0, s[84:85]
	global_load_dwordx4 v[210:213], v[178:179], off
	v_lshl_add_u64 v[178:179], v[178:179], 0, s[84:85]
	global_load_dwordx4 v[216:219], v[178:179], off
	v_lshl_add_u64 v[178:179], v[178:179], 0, s[84:85]
	global_load_dwordx4 v[220:223], v[178:179], off
	v_lshl_add_u64 v[178:179], v[178:179], 0, s[84:85]
	global_load_dwordx4 v[224:227], v[178:179], off
	v_lshl_add_u64 v[178:179], v[178:179], 0, s[84:85]
	global_load_dwordx4 v[238:241], v[178:179], off
	v_lshl_add_u64 v[178:179], v[178:179], 0, s[84:85]
	global_load_dwordx4 v[242:245], v[178:179], off
	v_lshl_add_u64 v[178:179], v[178:179], 0, s[84:85]
	global_load_dwordx4 v[246:249], v[178:179], off
	v_lshl_add_u64 v[178:179], v[178:179], 0, s[84:85]
	global_load_dwordx4 v[230:233], v[178:179], off
	v_lshl_add_u64 v[178:179], v[178:179], 0, s[84:85]
	global_load_dwordx4 v[148:151], v[178:179], off
	v_lshl_add_u64 v[178:179], v[178:179], 0, s[84:85]
	global_load_dwordx4 v[152:155], v[178:179], off
	v_lshl_add_u64 v[178:179], v[178:179], 0, s[84:85]
	global_load_dwordx4 v[166:169], v[178:179], off
	v_lshl_add_u64 v[178:179], v[178:179], 0, s[84:85]
	global_load_dwordx4 v[170:173], v[178:179], off
	v_mul_f32_e32 v132, v113, v113
	v_fmac_f32_e32 v132, v112, v112
	v_fmac_f32_e32 v132, v114, v114
	v_fmac_f32_e32 v132, v115, v115
	v_fmac_f32_e32 v132, v116, v116
	v_fmac_f32_e32 v132, v117, v117
	v_fmac_f32_e32 v132, v118, v118
	v_fmac_f32_e32 v132, v119, v119
	v_fmac_f32_e32 v132, v120, v120
	v_fmac_f32_e32 v132, v121, v121
	v_fmac_f32_e32 v132, v122, v122
	v_fmac_f32_e32 v132, v123, v123
	v_fmac_f32_e32 v132, v124, v124
	v_fmac_f32_e32 v132, v125, v125
	v_fmac_f32_e32 v132, v126, v126
	v_fmac_f32_e32 v132, v127, v127
	v_fmac_f32_e32 v132, v96, v96
	v_fmac_f32_e32 v132, v97, v97
	v_fmac_f32_e32 v132, v98, v98
	v_fmac_f32_e32 v132, v99, v99
	v_fmac_f32_e32 v132, v100, v100
	v_fmac_f32_e32 v132, v101, v101
	v_fmac_f32_e32 v132, v102, v102
	v_fmac_f32_e32 v132, v103, v103
	v_fmac_f32_e32 v132, v104, v104
	v_fmac_f32_e32 v132, v105, v105
	v_fmac_f32_e32 v132, v106, v106
	v_fmac_f32_e32 v132, v107, v107
	v_fmac_f32_e32 v132, v108, v108
	v_fmac_f32_e32 v132, v109, v109
	v_fmac_f32_e32 v132, v110, v110
	v_fmac_f32_e32 v132, v111, v111
	v_fmac_f32_e32 v132, v80, v80
	v_fmac_f32_e32 v132, v81, v81
	v_fmac_f32_e32 v132, v82, v82
	v_fmac_f32_e32 v132, v83, v83
	v_fmac_f32_e32 v132, v84, v84
	v_fmac_f32_e32 v132, v85, v85
	v_fmac_f32_e32 v132, v86, v86
	v_fmac_f32_e32 v132, v87, v87
	v_fmac_f32_e32 v132, v88, v88
	v_fmac_f32_e32 v132, v89, v89
	v_fmac_f32_e32 v132, v90, v90
	v_fmac_f32_e32 v132, v91, v91
	v_fmac_f32_e32 v132, v92, v92
	v_fmac_f32_e32 v132, v93, v93
	v_fmac_f32_e32 v132, v94, v94
	v_fmac_f32_e32 v132, v95, v95
	v_fmac_f32_e32 v132, v48, v48
	v_fmac_f32_e32 v132, v49, v49
	v_fmac_f32_e32 v132, v50, v50
	v_fmac_f32_e32 v132, v51, v51
	v_fmac_f32_e32 v132, v52, v52
	v_fmac_f32_e32 v132, v53, v53
	v_fmac_f32_e32 v132, v54, v54
	v_fmac_f32_e32 v132, v55, v55
	v_fmac_f32_e32 v132, v56, v56
	v_fmac_f32_e32 v132, v57, v57
	v_fmac_f32_e32 v132, v58, v58
	v_fmac_f32_e32 v132, v59, v59
	v_fmac_f32_e32 v132, v60, v60
	v_fmac_f32_e32 v132, v61, v61
	v_fmac_f32_e32 v132, v62, v62
	v_fmac_f32_e32 v132, v63, v63
	v_fmac_f32_e32 v132, v64, v64
	v_fmac_f32_e32 v132, v65, v65
	v_fmac_f32_e32 v132, v66, v66
	v_fmac_f32_e32 v132, v67, v67
	v_fmac_f32_e32 v132, v68, v68
	v_fmac_f32_e32 v132, v69, v69
	v_fmac_f32_e32 v132, v70, v70
	v_fmac_f32_e32 v132, v71, v71
	v_fmac_f32_e32 v132, v72, v72
	v_fmac_f32_e32 v132, v73, v73
	v_fmac_f32_e32 v132, v74, v74
	v_fmac_f32_e32 v132, v75, v75
	v_fmac_f32_e32 v132, v76, v76
	v_fmac_f32_e32 v132, v77, v77
	v_fmac_f32_e32 v132, v78, v78
	v_fmac_f32_e32 v132, v79, v79
	s_movk_i32 s8, 0xe0
	v_ashrrev_i32_e32 v209, 31, v208
	v_fmac_f32_e32 v132, v32, v32
	s_load_dwordx2 s[8:9], s[12:13], s8
	s_waitcnt lgkmcnt(0)
	v_lshl_add_u64 v[144:145], v[208:209], 1, v[128:129]
	v_fmac_f32_e32 v132, v33, v33
	s_barrier
	s_waitcnt vmcnt(15)
	ds_write_b128 v207, v[188:191]
	s_waitcnt vmcnt(14)
	ds_write_b128 v207, v[192:195] offset:1056
	s_waitcnt vmcnt(13)
	ds_write_b128 v207, v[196:199] offset:2112
	s_waitcnt vmcnt(12)
	ds_write_b128 v207, v[202:205] offset:3168
	s_waitcnt vmcnt(11)
	ds_write_b128 v207, v[210:213] offset:4224
	s_waitcnt vmcnt(10)
	ds_write_b128 v207, v[216:219] offset:5280
	s_waitcnt vmcnt(9)
	ds_write_b128 v207, v[220:223] offset:6336
	s_waitcnt vmcnt(8)
	ds_write_b128 v207, v[224:227] offset:7392
	s_waitcnt vmcnt(7)
	ds_write_b128 v207, v[238:241] offset:8448
	s_waitcnt vmcnt(6)
	ds_write_b128 v207, v[242:245] offset:9504
	s_waitcnt vmcnt(5)
	ds_write_b128 v207, v[246:249] offset:10560
	s_waitcnt vmcnt(4)
	ds_write_b128 v207, v[230:233] offset:11616
	s_waitcnt vmcnt(3)
	ds_write_b128 v207, v[148:151] offset:12672
	s_waitcnt vmcnt(2)
	ds_write_b128 v207, v[152:155] offset:13728
	s_waitcnt vmcnt(1)
	ds_write_b128 v207, v[166:169] offset:14784
	s_waitcnt vmcnt(0)
	ds_write_b128 v207, v[170:173] offset:15840
	s_waitcnt lgkmcnt(8)
	s_waitcnt lgkmcnt(0)
	ds_read_b128 v[188:191], v206 offset:0
	ds_read_b128 v[192:195], v206 offset:32
	ds_read_b128 v[196:199], v206 offset:64
	ds_read_b128 v[202:205], v206 offset:96
	ds_read_b128 v[210:213], v206 offset:128
	ds_read_b128 v[216:219], v206 offset:160
	ds_read_b128 v[220:223], v206 offset:192
	ds_read_b128 v[224:227], v206 offset:224
	v_fmac_f32_e32 v132, v34, v34
	v_fmac_f32_e32 v132, v35, v35
	v_fmac_f32_e32 v132, v36, v36
	v_fmac_f32_e32 v132, v37, v37
	v_fmac_f32_e32 v132, v38, v38
	v_fmac_f32_e32 v132, v39, v39
	v_fmac_f32_e32 v132, v40, v40
	v_fmac_f32_e32 v132, v41, v41
	v_fmac_f32_e32 v132, v42, v42
	v_fmac_f32_e32 v132, v43, v43
	v_fmac_f32_e32 v132, v44, v44
	s_add_u32 s8, s8, s18
	v_fmac_f32_e32 v132, v45, v45
	s_addc_u32 s9, s9, s19
	s_lshl_b32 s10, s36, 10
	v_fmac_f32_e32 v132, v46, v46
	s_add_u32 s8, s8, s10
	v_fmac_f32_e32 v132, v47, v47
	s_addc_u32 s9, s9, 0
	v_fmac_f32_e32 v132, v16, v16
	v_lshl_add_u64 v[146:147], v[208:209], 2, s[8:9]
	v_fmac_f32_e32 v132, v17, v17
	global_load_dwordx4 v[158:161], v[146:147], off
	global_load_dwordx4 v[162:165], v[146:147], off offset:32
	v_fmac_f32_e32 v132, v18, v18
	v_fmac_f32_e32 v132, v19, v19
	v_fmac_f32_e32 v132, v20, v20
	v_fmac_f32_e32 v132, v21, v21
	v_fmac_f32_e32 v132, v22, v22
	v_fmac_f32_e32 v132, v23, v23
	v_fmac_f32_e32 v132, v24, v24
	v_fmac_f32_e32 v132, v25, v25
	v_fmac_f32_e32 v132, v26, v26
	v_fmac_f32_e32 v132, v27, v27
	v_fmac_f32_e32 v132, v28, v28
	v_fmac_f32_e32 v132, v29, v29
	v_fmac_f32_e32 v132, v30, v30
	v_fmac_f32_e32 v132, v31, v31
	v_fmac_f32_e32 v132, v0, v0
	v_fmac_f32_e32 v132, v1, v1
	v_fmac_f32_e32 v132, v2, v2
	v_fmac_f32_e32 v132, v3, v3
	v_fmac_f32_e32 v132, v4, v4
	v_fmac_f32_e32 v132, v5, v5
	v_fmac_f32_e32 v132, v6, v6
	v_fmac_f32_e32 v132, v7, v7
	v_fmac_f32_e32 v132, v8, v8
	v_fmac_f32_e32 v132, v9, v9
	v_fmac_f32_e32 v132, v10, v10
	v_fmac_f32_e32 v132, v11, v11
	v_pk_mul_f32 v[130:131], v[12:13], v[12:13]
	v_pk_mul_f32 v[128:129], v[14:15], v[14:15]
	v_add_f32_e32 v130, v130, v132
	v_add_f32_e32 v130, v131, v130
	v_add_f32_e32 v128, v128, v130
	v_add_f32_e32 v128, v129, v128
	v_xor_b32_e32 v129, 0x80, v215
	ds_bpermute_b32 v129, v129, v128
	s_waitcnt lgkmcnt(8)
	v_permlane32_swap_b32_e32 v188, v190
	v_permlane32_swap_b32_e32 v189, v191
	s_waitcnt lgkmcnt(7)
	v_permlane32_swap_b32_e32 v192, v194
	v_permlane32_swap_b32_e32 v193, v195
	s_waitcnt lgkmcnt(6)
	v_permlane32_swap_b32_e32 v196, v198
	v_permlane32_swap_b32_e32 v197, v199
	s_waitcnt lgkmcnt(5)
	v_permlane32_swap_b32_e32 v202, v204
	v_permlane32_swap_b32_e32 v203, v205
	v_mov_b64_e32 v[174:175], v[188:189]
	v_mov_b64_e32 v[176:177], v[190:191]
	v_mov_b64_e32 v[178:179], v[192:193]
	v_mov_b64_e32 v[180:181], v[194:195]
	v_mov_b64_e32 v[154:155], v[196:197]
	v_mov_b64_e32 v[152:153], v[198:199]
	v_mov_b64_e32 v[150:151], v[202:203]
	v_mov_b64_e32 v[148:149], v[204:205]
	global_load_dwordx4 v[166:169], v[146:147], off offset:64
	global_load_dwordx4 v[170:173], v[146:147], off offset:96
	global_load_dwordx4 v[140:143], v[146:147], off offset:128
	global_load_dwordx4 v[136:139], v[146:147], off offset:160
	s_add_i32 s74, s74, s48
	s_add_i32 s73, s73, s48
	s_cmpk_gt_i32 s74, 0xff
	s_waitcnt lgkmcnt(0)
	v_add_f32_e32 v128, v128, v129
	v_fmamk_f32 v128, v128, 0x3b800000, v228
	v_mul_f32_e32 v129, 0x4f800000, v128
	v_cmp_gt_f32_e32 vcc, s1, v128
	v_lshlrev_b32_e32 v157, 16, v174
	v_cndmask_b32_e32 v128, v128, v129, vcc
	v_sqrt_f32_e32 v129, v128
	v_and_b32_e32 v174, 0xffff0000, v174
	v_mul_f32_e32 v183, 0xbfb8aa3b, v174
	v_exp_f32_e32 v183, v183
	v_add_u32_e32 v130, -1, v129
	v_fma_f32 v131, -v130, v129, v128
	v_cmp_ge_f32_e64 s[8:9], 0, v131
	v_add_u32_e32 v131, 1, v129
	s_nop 0
	v_cndmask_b32_e64 v130, v129, v130, s[8:9]
	v_fma_f32 v129, -v131, v129, v128
	v_cmp_lt_f32_e64 s[8:9], 0, v129
	s_nop 1
	v_cndmask_b32_e64 v129, v130, v131, s[8:9]
	v_mul_f32_e32 v130, 0x37800000, v129
	v_cndmask_b32_e32 v129, v129, v130, vcc
	v_cmp_class_f32_e32 vcc, v128, v229
	s_nop 1
	v_cndmask_b32_e32 v128, v129, v128, vcc
	v_div_scale_f32 v129, s[8:9], v128, v128, 1.0
	v_rcp_f32_e32 v130, v129
	s_nop 0
	v_fma_f32 v131, -v129, v130, 1.0
	v_fmac_f32_e32 v130, v131, v130
	v_div_scale_f32 v131, vcc, 1.0, v128, 1.0
	v_mul_f32_e32 v132, v131, v130
	v_fma_f32 v133, -v129, v132, v131
	v_fmac_f32_e32 v132, v133, v130
	v_fma_f32 v129, -v129, v132, v131
	v_div_fmas_f32 v129, v129, v130, v132
	v_div_fixup_f32 v156, v129, v128, 1.0
	v_mul_f32_e32 v128, 0xbfb8aa3b, v157
	v_exp_f32_e32 v182, v128
	global_load_dwordx4 v[132:135], v[146:147], off offset:192
	global_load_dwordx4 v[128:131], v[146:147], off offset:224
	v_add_f32_e32 v182, 1.0, v182
	v_rcp_f32_e32 v182, v182
	s_nop 0
	v_mul_f32_e32 v157, v182, v157
	v_mul_f32_e32 v112, v112, v157
	v_add_f32_e32 v157, 1.0, v183
	v_rcp_f32_e32 v157, v157
	v_mul_f32_e32 v112, v156, v112
	v_lshlrev_b32_e32 v182, 16, v175
	v_mul_f32_e32 v183, 0xbfb8aa3b, v182
	s_waitcnt vmcnt(7)
	v_mul_f32_e32 v112, v158, v112
	v_and_b32_e32 v158, 0xffff0000, v175
	v_exp_f32_e32 v183, v183
	v_mul_f32_e32 v157, v157, v174
	v_mul_f32_e32 v174, 0xbfb8aa3b, v158
	v_exp_f32_e32 v174, v174
	v_mul_f32_e32 v113, v113, v157
	v_add_f32_e32 v157, 1.0, v183
	v_mul_f32_e32 v113, v156, v113
	v_rcp_f32_e32 v157, v157
	v_mul_f32_e32 v113, v159, v113
	v_add_f32_e32 v159, 1.0, v174
	v_rcp_f32_e32 v159, v159
	v_mul_f32_e32 v157, v157, v182
	v_mul_f32_e32 v114, v114, v157
	v_mul_f32_e32 v114, v156, v114
	v_mul_f32_e32 v157, v159, v158
	v_mul_f32_e32 v115, v115, v157
	v_lshlrev_b32_e32 v157, 16, v176
	v_mul_f32_e32 v158, 0xbfb8aa3b, v157
	v_exp_f32_e32 v158, v158
	v_mul_f32_e32 v115, v156, v115
	v_mul_f32_e32 v114, v160, v114
	v_mul_f32_e32 v115, v161, v115
	v_cvt_pk_bf16_f32 v112, v112, v113
	v_cvt_pk_bf16_f32 v113, v114, v115
	v_mov_b64_e32 v[238:239], v[112:113]
	v_add_f32_e32 v112, 1.0, v158
	v_and_b32_e32 v113, 0xffff0000, v176
	v_rcp_f32_e32 v112, v112
	v_mul_f32_e32 v114, 0xbfb8aa3b, v113
	v_exp_f32_e32 v114, v114
	v_lshlrev_b32_e32 v115, 16, v177
	v_mul_f32_e32 v112, v112, v157
	v_mul_f32_e32 v112, v116, v112
	v_add_f32_e32 v114, 1.0, v114
	v_mul_f32_e32 v116, 0xbfb8aa3b, v115
	v_rcp_f32_e32 v114, v114
	v_exp_f32_e32 v116, v116
	v_mul_f32_e32 v112, v156, v112
	s_waitcnt vmcnt(6)
	v_mul_f32_e32 v112, v162, v112
	v_mul_f32_e32 v113, v114, v113
	v_add_f32_e32 v114, 1.0, v116
	v_and_b32_e32 v116, 0xffff0000, v177
	v_mul_f32_e32 v113, v117, v113
	v_mul_f32_e32 v117, 0xbfb8aa3b, v116
	v_rcp_f32_e32 v114, v114
	v_exp_f32_e32 v117, v117
	v_mul_f32_e32 v113, v156, v113
	v_mul_f32_e32 v113, v163, v113
	v_mul_f32_e32 v114, v114, v115
	v_add_f32_e32 v115, 1.0, v117
	v_rcp_f32_e32 v115, v115
	v_mul_f32_e32 v114, v118, v114
	v_mul_f32_e32 v114, v156, v114
	v_mul_f32_e32 v114, v164, v114
	v_mul_f32_e32 v115, v115, v116
	v_lshlrev_b32_e32 v116, 16, v178
	v_mul_f32_e32 v117, 0xbfb8aa3b, v116
	v_mul_f32_e32 v115, v119, v115
	v_exp_f32_e32 v117, v117
	v_mul_f32_e32 v115, v156, v115
	v_mul_f32_e32 v115, v165, v115
	v_cvt_pk_bf16_f32 v112, v112, v113
	v_cvt_pk_bf16_f32 v113, v114, v115
	v_mov_b64_e32 v[240:241], v[112:113]
	s_nop 1
	v_permlane32_swap_b32_e32 v238, v240
	v_permlane32_swap_b32_e32 v239, v241
	ds_write_b128 v206, v[238:241] offset:0
	v_and_b32_e32 v113, 0xffff0000, v178
	v_add_f32_e32 v112, 1.0, v117
	v_mul_f32_e32 v114, 0xbfb8aa3b, v113
	v_rcp_f32_e32 v112, v112
	v_exp_f32_e32 v114, v114
	v_lshlrev_b32_e32 v115, 16, v179
	v_mul_f32_e32 v112, v112, v116
	v_add_f32_e32 v114, 1.0, v114
	v_mul_f32_e32 v116, 0xbfb8aa3b, v115
	v_rcp_f32_e32 v114, v114
	v_exp_f32_e32 v116, v116
	v_mul_f32_e32 v112, v120, v112
	v_mul_f32_e32 v112, v156, v112
	v_mul_f32_e32 v113, v114, v113
	v_add_f32_e32 v114, 1.0, v116
	v_and_b32_e32 v116, 0xffff0000, v179
	v_mul_f32_e32 v117, 0xbfb8aa3b, v116
	v_rcp_f32_e32 v114, v114
	v_exp_f32_e32 v117, v117
	v_mul_f32_e32 v113, v121, v113
	v_mul_f32_e32 v113, v156, v113
	v_mul_f32_e32 v114, v114, v115
	v_add_f32_e32 v115, 1.0, v117
	v_rcp_f32_e32 v115, v115
	v_mul_f32_e32 v114, v122, v114
	s_waitcnt vmcnt(5)
	v_mul_f32_e32 v112, v166, v112
	v_mul_f32_e32 v113, v167, v113
	v_mul_f32_e32 v115, v115, v116
	v_lshlrev_b32_e32 v116, 16, v180
	v_mul_f32_e32 v117, 0xbfb8aa3b, v116
	v_mul_f32_e32 v115, v123, v115
	v_exp_f32_e32 v117, v117
	v_mul_f32_e32 v114, v156, v114
	v_mul_f32_e32 v115, v156, v115
	v_mul_f32_e32 v114, v168, v114
	v_mul_f32_e32 v115, v169, v115
	v_cvt_pk_bf16_f32 v112, v112, v113
	v_cvt_pk_bf16_f32 v113, v114, v115
	v_mov_b64_e32 v[242:243], v[112:113]
	v_and_b32_e32 v113, 0xffff0000, v180
	v_add_f32_e32 v112, 1.0, v117
	v_mul_f32_e32 v114, 0xbfb8aa3b, v113
	v_rcp_f32_e32 v112, v112
	v_exp_f32_e32 v114, v114
	v_lshlrev_b32_e32 v115, 16, v181
	v_mul_f32_e32 v112, v112, v116
	v_add_f32_e32 v114, 1.0, v114
	v_mul_f32_e32 v116, 0xbfb8aa3b, v115
	v_rcp_f32_e32 v114, v114
	v_exp_f32_e32 v116, v116
	v_mul_f32_e32 v112, v124, v112
	v_mul_f32_e32 v112, v156, v112
	v_mul_f32_e32 v113, v114, v113
	v_add_f32_e32 v114, 1.0, v116
	v_and_b32_e32 v116, 0xffff0000, v181
	v_mul_f32_e32 v117, 0xbfb8aa3b, v116
	v_rcp_f32_e32 v114, v114
	v_exp_f32_e32 v117, v117
	v_mul_f32_e32 v113, v125, v113
	v_mul_f32_e32 v113, v156, v113
	v_mul_f32_e32 v114, v114, v115
	v_add_f32_e32 v115, 1.0, v117
	v_rcp_f32_e32 v115, v115
	v_mul_f32_e32 v114, v126, v114
	s_waitcnt vmcnt(4)
	v_mul_f32_e32 v112, v170, v112
	v_mul_f32_e32 v113, v171, v113
	v_mul_f32_e32 v115, v115, v116
	v_lshlrev_b32_e32 v116, 16, v154
	v_mul_f32_e32 v117, 0xbfb8aa3b, v116
	v_exp_f32_e32 v117, v117
	v_mul_f32_e32 v115, v127, v115
	v_mul_f32_e32 v114, v156, v114
	v_mul_f32_e32 v115, v156, v115
	v_mul_f32_e32 v114, v172, v114
	v_mul_f32_e32 v115, v173, v115
	v_cvt_pk_bf16_f32 v112, v112, v113
	v_cvt_pk_bf16_f32 v113, v114, v115
	v_mov_b64_e32 v[244:245], v[112:113]
	s_nop 1
	v_permlane32_swap_b32_e32 v242, v244
	v_permlane32_swap_b32_e32 v243, v245
	ds_write_b128 v206, v[242:245] offset:32
	v_add_f32_e32 v112, 1.0, v117
	v_and_b32_e32 v113, 0xffff0000, v154
	v_rcp_f32_e32 v112, v112
	v_mul_f32_e32 v114, 0xbfb8aa3b, v113
	v_exp_f32_e32 v114, v114
	v_mul_f32_e32 v112, v112, v116
	v_mul_f32_e32 v96, v96, v112
	v_add_f32_e32 v112, 1.0, v114
	v_lshlrev_b32_e32 v114, 16, v155
	v_rcp_f32_e32 v112, v112
	v_mul_f32_e32 v115, 0xbfb8aa3b, v114
	v_exp_f32_e32 v115, v115
	v_mul_f32_e32 v96, v156, v96
	v_mul_f32_e32 v112, v112, v113
	v_and_b32_e32 v113, 0xffff0000, v155
	v_mul_f32_e32 v97, v97, v112
	v_add_f32_e32 v112, 1.0, v115
	v_mul_f32_e32 v115, 0xbfb8aa3b, v113
	v_rcp_f32_e32 v112, v112
	v_exp_f32_e32 v115, v115
	v_mul_f32_e32 v97, v156, v97
	s_waitcnt vmcnt(3)
	v_mul_f32_e32 v96, v140, v96
	v_mul_f32_e32 v112, v112, v114
	v_add_f32_e32 v114, 1.0, v115
	v_rcp_f32_e32 v114, v114
	v_mul_f32_e32 v98, v98, v112
	v_mul_f32_e32 v97, v141, v97
	v_mul_f32_e32 v98, v156, v98
	v_mul_f32_e32 v112, v114, v113
	v_mul_f32_e32 v99, v99, v112
	v_lshlrev_b32_e32 v112, 16, v152
	v_mul_f32_e32 v113, 0xbfb8aa3b, v112
	v_exp_f32_e32 v113, v113
	v_mul_f32_e32 v99, v156, v99
	v_mul_f32_e32 v98, v142, v98
	v_mul_f32_e32 v99, v143, v99
	v_cvt_pk_bf16_f32 v96, v96, v97
	v_cvt_pk_bf16_f32 v97, v98, v99
	v_mov_b64_e32 v[246:247], v[96:97]
	v_add_f32_e32 v96, 1.0, v113
	v_and_b32_e32 v97, 0xffff0000, v152
	v_rcp_f32_e32 v96, v96
	v_mul_f32_e32 v98, 0xbfb8aa3b, v97
	v_exp_f32_e32 v98, v98
	v_lshlrev_b32_e32 v99, 16, v153
	v_mul_f32_e32 v96, v96, v112
	v_mul_f32_e32 v96, v100, v96
	v_add_f32_e32 v98, 1.0, v98
	v_mul_f32_e32 v100, 0xbfb8aa3b, v99
	v_rcp_f32_e32 v98, v98
	v_exp_f32_e32 v100, v100
	v_mul_f32_e32 v96, v156, v96
	s_waitcnt vmcnt(2)
	v_mul_f32_e32 v96, v136, v96
	v_mul_f32_e32 v97, v98, v97
	v_add_f32_e32 v98, 1.0, v100
	v_and_b32_e32 v100, 0xffff0000, v153
	v_mul_f32_e32 v97, v101, v97
	v_mul_f32_e32 v101, 0xbfb8aa3b, v100
	v_rcp_f32_e32 v98, v98
	v_exp_f32_e32 v101, v101
	v_mul_f32_e32 v97, v156, v97
	v_mul_f32_e32 v97, v137, v97
	v_mul_f32_e32 v98, v98, v99
	v_add_f32_e32 v99, 1.0, v101
	v_rcp_f32_e32 v99, v99
	v_mul_f32_e32 v98, v102, v98
	v_mul_f32_e32 v98, v156, v98
	v_mul_f32_e32 v98, v138, v98
	v_mul_f32_e32 v99, v99, v100
	v_lshlrev_b32_e32 v100, 16, v150
	v_mul_f32_e32 v101, 0xbfb8aa3b, v100
	v_mul_f32_e32 v99, v103, v99
	v_exp_f32_e32 v101, v101
	v_mul_f32_e32 v99, v156, v99
	v_mul_f32_e32 v99, v139, v99
	v_cvt_pk_bf16_f32 v96, v96, v97
	v_cvt_pk_bf16_f32 v97, v98, v99
	v_mov_b64_e32 v[248:249], v[96:97]
	s_nop 1
	v_permlane32_swap_b32_e32 v246, v248
	v_permlane32_swap_b32_e32 v247, v249
	ds_write_b128 v206, v[246:249] offset:64
	v_and_b32_e32 v97, 0xffff0000, v150
	v_add_f32_e32 v96, 1.0, v101
	v_mul_f32_e32 v98, 0xbfb8aa3b, v97
	v_rcp_f32_e32 v96, v96
	v_exp_f32_e32 v98, v98
	v_lshlrev_b32_e32 v99, 16, v151
	v_mul_f32_e32 v96, v96, v100
	v_add_f32_e32 v98, 1.0, v98
	v_mul_f32_e32 v100, 0xbfb8aa3b, v99
	v_rcp_f32_e32 v98, v98
	v_exp_f32_e32 v100, v100
	v_mul_f32_e32 v96, v104, v96
	v_mul_f32_e32 v96, v156, v96
	v_mul_f32_e32 v97, v98, v97
	v_add_f32_e32 v98, 1.0, v100
	v_and_b32_e32 v100, 0xffff0000, v151
	v_mul_f32_e32 v101, 0xbfb8aa3b, v100
	v_rcp_f32_e32 v98, v98
	v_exp_f32_e32 v101, v101
	v_mul_f32_e32 v97, v105, v97
	v_mul_f32_e32 v97, v156, v97
	v_mul_f32_e32 v98, v98, v99
	v_add_f32_e32 v99, 1.0, v101
	v_rcp_f32_e32 v99, v99
	v_mul_f32_e32 v98, v106, v98
	s_waitcnt vmcnt(1)
	v_mul_f32_e32 v96, v132, v96
	v_mul_f32_e32 v97, v133, v97
	v_mul_f32_e32 v99, v99, v100
	v_lshlrev_b32_e32 v100, 16, v148
	v_mul_f32_e32 v101, 0xbfb8aa3b, v100
	v_mul_f32_e32 v99, v107, v99
	v_exp_f32_e32 v101, v101
	v_mul_f32_e32 v98, v156, v98
	v_mul_f32_e32 v99, v156, v99
	v_mul_f32_e32 v98, v134, v98
	v_mul_f32_e32 v99, v135, v99
	v_cvt_pk_bf16_f32 v96, v96, v97
	v_cvt_pk_bf16_f32 v97, v98, v99
	v_mov_b64_e32 v[230:231], v[96:97]
	v_and_b32_e32 v97, 0xffff0000, v148
	v_add_f32_e32 v96, 1.0, v101
	v_mul_f32_e32 v98, 0xbfb8aa3b, v97
	v_rcp_f32_e32 v96, v96
	v_exp_f32_e32 v98, v98
	v_lshlrev_b32_e32 v99, 16, v149
	v_mul_f32_e32 v96, v96, v100
	v_add_f32_e32 v98, 1.0, v98
	v_mul_f32_e32 v100, 0xbfb8aa3b, v99
	v_rcp_f32_e32 v98, v98
	v_exp_f32_e32 v100, v100
	v_mul_f32_e32 v96, v108, v96
	v_mul_f32_e32 v96, v156, v96
	v_mul_f32_e32 v97, v98, v97
	v_add_f32_e32 v98, 1.0, v100
	v_and_b32_e32 v100, 0xffff0000, v149
	v_mul_f32_e32 v101, 0xbfb8aa3b, v100
	v_rcp_f32_e32 v98, v98
	v_exp_f32_e32 v101, v101
	v_mul_f32_e32 v97, v109, v97
	v_mul_f32_e32 v97, v156, v97
	v_mul_f32_e32 v98, v98, v99
	v_add_f32_e32 v99, 1.0, v101
	v_rcp_f32_e32 v99, v99
	v_mul_f32_e32 v98, v110, v98
	s_waitcnt vmcnt(0)
	v_mul_f32_e32 v96, v128, v96
	v_mul_f32_e32 v97, v129, v97
	v_mul_f32_e32 v99, v99, v100
	v_mul_f32_e32 v99, v111, v99
	v_mul_f32_e32 v98, v156, v98
	v_mul_f32_e32 v99, v156, v99
	v_mul_f32_e32 v98, v130, v98
	v_mul_f32_e32 v99, v131, v99
	v_cvt_pk_bf16_f32 v96, v96, v97
	v_cvt_pk_bf16_f32 v97, v98, v99
	v_permlane32_swap_b32_e32 v210, v212
	v_permlane32_swap_b32_e32 v211, v213
	v_permlane32_swap_b32_e32 v216, v218
	v_permlane32_swap_b32_e32 v217, v219
	v_permlane32_swap_b32_e32 v220, v222
	v_permlane32_swap_b32_e32 v221, v223
	v_permlane32_swap_b32_e32 v224, v226
	v_permlane32_swap_b32_e32 v225, v227
	v_mov_b64_e32 v[136:137], v[210:211]
	v_mov_b64_e32 v[138:139], v[212:213]
	v_mov_b64_e32 v[140:141], v[216:217]
	v_mov_b64_e32 v[142:143], v[218:219]
	v_mov_b64_e32 v[118:119], v[220:221]
	v_mov_b64_e32 v[116:117], v[222:223]
	v_mov_b64_e32 v[114:115], v[224:225]
	v_mov_b64_e32 v[112:113], v[226:227]
	ds_read_b128 v[188:191], v206 offset:256
	ds_read_b128 v[192:195], v206 offset:288
	ds_read_b128 v[196:199], v206 offset:320
	ds_read_b128 v[202:205], v206 offset:352
	v_lshlrev_b32_e32 v148, 16, v136
	v_mov_b64_e32 v[232:233], v[96:97]
	s_nop 1
	v_permlane32_swap_b32_e32 v230, v232
	v_permlane32_swap_b32_e32 v231, v233
	ds_write_b128 v206, v[230:233] offset:96
	global_load_dwordx4 v[120:123], v[146:147], off offset:256
	global_load_dwordx4 v[124:127], v[146:147], off offset:288
	global_load_dwordx4 v[128:131], v[146:147], off offset:320
	global_load_dwordx4 v[132:135], v[146:147], off offset:352
	global_load_dwordx4 v[108:111], v[146:147], off offset:384
	global_load_dwordx4 v[104:107], v[146:147], off offset:416
	v_mul_f32_e32 v96, 0xbfb8aa3b, v148
	v_exp_f32_e32 v149, v96
	v_and_b32_e32 v136, 0xffff0000, v136
	v_mul_f32_e32 v150, 0xbfb8aa3b, v136
	v_exp_f32_e32 v150, v150
	v_add_f32_e32 v149, 1.0, v149
	v_rcp_f32_e32 v149, v149
	global_load_dwordx4 v[100:103], v[146:147], off offset:448
	global_load_dwordx4 v[96:99], v[146:147], off offset:480
	v_mul_f32_e32 v148, v149, v148
	v_mul_f32_e32 v80, v80, v148
	v_add_f32_e32 v148, 1.0, v150
	v_rcp_f32_e32 v148, v148
	v_mul_f32_e32 v80, v156, v80
	v_lshlrev_b32_e32 v149, 16, v137
	v_mul_f32_e32 v150, 0xbfb8aa3b, v149
	v_exp_f32_e32 v150, v150
	s_waitcnt vmcnt(7)
	v_mul_f32_e32 v80, v120, v80
	v_mul_f32_e32 v120, v148, v136
	v_and_b32_e32 v136, 0xffff0000, v137
	v_mul_f32_e32 v137, 0xbfb8aa3b, v136
	v_exp_f32_e32 v137, v137
	v_mul_f32_e32 v81, v81, v120
	v_add_f32_e32 v120, 1.0, v150
	v_mul_f32_e32 v81, v156, v81
	v_rcp_f32_e32 v120, v120
	v_mul_f32_e32 v81, v121, v81
	v_add_f32_e32 v121, 1.0, v137
	v_rcp_f32_e32 v121, v121
	v_mul_f32_e32 v120, v120, v149
	v_mul_f32_e32 v82, v82, v120
	v_mul_f32_e32 v82, v156, v82
	v_mul_f32_e32 v120, v121, v136
	v_mul_f32_e32 v83, v83, v120
	v_lshlrev_b32_e32 v120, 16, v138
	v_mul_f32_e32 v121, 0xbfb8aa3b, v120
	v_exp_f32_e32 v121, v121
	v_mul_f32_e32 v83, v156, v83
	v_mul_f32_e32 v82, v122, v82
	v_mul_f32_e32 v83, v123, v83
	v_cvt_pk_bf16_f32 v80, v80, v81
	v_cvt_pk_bf16_f32 v81, v82, v83
	v_mov_b64_e32 v[238:239], v[80:81]
	v_add_f32_e32 v80, 1.0, v121
	v_and_b32_e32 v81, 0xffff0000, v138
	v_rcp_f32_e32 v80, v80
	v_mul_f32_e32 v82, 0xbfb8aa3b, v81
	v_exp_f32_e32 v82, v82
	v_lshlrev_b32_e32 v83, 16, v139
	v_mul_f32_e32 v80, v80, v120
	v_mul_f32_e32 v80, v84, v80
	v_add_f32_e32 v82, 1.0, v82
	v_mul_f32_e32 v84, 0xbfb8aa3b, v83
	v_rcp_f32_e32 v82, v82
	v_exp_f32_e32 v84, v84
	v_mul_f32_e32 v80, v156, v80
	s_waitcnt vmcnt(6)
	v_mul_f32_e32 v80, v124, v80
	v_mul_f32_e32 v81, v82, v81
	v_add_f32_e32 v82, 1.0, v84
	v_and_b32_e32 v84, 0xffff0000, v139
	v_mul_f32_e32 v81, v85, v81
	v_mul_f32_e32 v85, 0xbfb8aa3b, v84
	v_rcp_f32_e32 v82, v82
	v_exp_f32_e32 v85, v85
	v_mul_f32_e32 v81, v156, v81
	v_mul_f32_e32 v81, v125, v81
	v_mul_f32_e32 v82, v82, v83
	v_add_f32_e32 v83, 1.0, v85
	v_rcp_f32_e32 v83, v83
	v_mul_f32_e32 v82, v86, v82
	v_mul_f32_e32 v82, v156, v82
	v_mul_f32_e32 v82, v126, v82
	v_mul_f32_e32 v83, v83, v84
	v_lshlrev_b32_e32 v84, 16, v140
	v_mul_f32_e32 v85, 0xbfb8aa3b, v84
	v_mul_f32_e32 v83, v87, v83
	v_exp_f32_e32 v85, v85
	v_mul_f32_e32 v83, v156, v83
	v_mul_f32_e32 v83, v127, v83
	v_cvt_pk_bf16_f32 v80, v80, v81
	v_cvt_pk_bf16_f32 v81, v82, v83
	v_mov_b64_e32 v[240:241], v[80:81]
	s_nop 1
	v_permlane32_swap_b32_e32 v238, v240
	v_permlane32_swap_b32_e32 v239, v241
	ds_write_b128 v206, v[238:241] offset:128
	v_and_b32_e32 v81, 0xffff0000, v140
	v_add_f32_e32 v80, 1.0, v85
	v_mul_f32_e32 v82, 0xbfb8aa3b, v81
	v_rcp_f32_e32 v80, v80
	v_exp_f32_e32 v82, v82
	v_lshlrev_b32_e32 v83, 16, v141
	v_mul_f32_e32 v80, v80, v84
	v_add_f32_e32 v82, 1.0, v82
	v_mul_f32_e32 v84, 0xbfb8aa3b, v83
	v_rcp_f32_e32 v82, v82
	v_exp_f32_e32 v84, v84
	v_mul_f32_e32 v80, v88, v80
	v_mul_f32_e32 v80, v156, v80
	v_mul_f32_e32 v81, v82, v81
	v_add_f32_e32 v82, 1.0, v84
	v_and_b32_e32 v84, 0xffff0000, v141
	v_mul_f32_e32 v85, 0xbfb8aa3b, v84
	v_rcp_f32_e32 v82, v82
	v_exp_f32_e32 v85, v85
	v_mul_f32_e32 v81, v89, v81
	v_mul_f32_e32 v81, v156, v81
	v_mul_f32_e32 v82, v82, v83
	v_add_f32_e32 v83, 1.0, v85
	v_rcp_f32_e32 v83, v83
	v_mul_f32_e32 v82, v90, v82
	s_waitcnt vmcnt(5)
	v_mul_f32_e32 v80, v128, v80
	v_mul_f32_e32 v81, v129, v81
	v_mul_f32_e32 v83, v83, v84
	v_lshlrev_b32_e32 v84, 16, v142
	v_mul_f32_e32 v85, 0xbfb8aa3b, v84
	v_mul_f32_e32 v83, v91, v83
	v_exp_f32_e32 v85, v85
	v_mul_f32_e32 v82, v156, v82
	v_mul_f32_e32 v83, v156, v83
	v_mul_f32_e32 v82, v130, v82
	v_mul_f32_e32 v83, v131, v83
	v_cvt_pk_bf16_f32 v80, v80, v81
	v_cvt_pk_bf16_f32 v81, v82, v83
	v_mov_b64_e32 v[242:243], v[80:81]
	v_and_b32_e32 v81, 0xffff0000, v142
	v_add_f32_e32 v80, 1.0, v85
	v_mul_f32_e32 v82, 0xbfb8aa3b, v81
	v_rcp_f32_e32 v80, v80
	v_exp_f32_e32 v82, v82
	v_lshlrev_b32_e32 v83, 16, v143
	v_mul_f32_e32 v80, v80, v84
	v_add_f32_e32 v82, 1.0, v82
	v_mul_f32_e32 v84, 0xbfb8aa3b, v83
	v_rcp_f32_e32 v82, v82
	v_exp_f32_e32 v84, v84
	v_mul_f32_e32 v80, v92, v80
	v_mul_f32_e32 v80, v156, v80
	v_mul_f32_e32 v81, v82, v81
	v_add_f32_e32 v82, 1.0, v84
	v_and_b32_e32 v84, 0xffff0000, v143
	v_mul_f32_e32 v85, 0xbfb8aa3b, v84
	v_rcp_f32_e32 v82, v82
	v_exp_f32_e32 v85, v85
	v_mul_f32_e32 v81, v93, v81
	v_mul_f32_e32 v81, v156, v81
	v_mul_f32_e32 v82, v82, v83
	v_add_f32_e32 v83, 1.0, v85
	v_rcp_f32_e32 v83, v83
	v_mul_f32_e32 v82, v94, v82
	s_waitcnt vmcnt(4)
	v_mul_f32_e32 v80, v132, v80
	v_mul_f32_e32 v81, v133, v81
	v_mul_f32_e32 v83, v83, v84
	v_lshlrev_b32_e32 v84, 16, v118
	v_mul_f32_e32 v85, 0xbfb8aa3b, v84
	v_exp_f32_e32 v85, v85
	v_mul_f32_e32 v83, v95, v83
	v_mul_f32_e32 v82, v156, v82
	v_mul_f32_e32 v83, v156, v83
	v_mul_f32_e32 v82, v134, v82
	v_mul_f32_e32 v83, v135, v83
	v_cvt_pk_bf16_f32 v80, v80, v81
	v_cvt_pk_bf16_f32 v81, v82, v83
	v_mov_b64_e32 v[244:245], v[80:81]
	s_nop 1
	v_permlane32_swap_b32_e32 v242, v244
	v_permlane32_swap_b32_e32 v243, v245
	ds_write_b128 v206, v[242:245] offset:160
	v_add_f32_e32 v80, 1.0, v85
	v_and_b32_e32 v81, 0xffff0000, v118
	v_rcp_f32_e32 v80, v80
	v_mul_f32_e32 v82, 0xbfb8aa3b, v81
	v_exp_f32_e32 v82, v82
	v_mul_f32_e32 v80, v80, v84
	v_mul_f32_e32 v48, v48, v80
	v_add_f32_e32 v80, 1.0, v82
	v_lshlrev_b32_e32 v82, 16, v119
	v_rcp_f32_e32 v80, v80
	v_mul_f32_e32 v83, 0xbfb8aa3b, v82
	v_exp_f32_e32 v83, v83
	v_mul_f32_e32 v48, v156, v48
	v_mul_f32_e32 v80, v80, v81
	v_and_b32_e32 v81, 0xffff0000, v119
	v_mul_f32_e32 v49, v49, v80
	v_add_f32_e32 v80, 1.0, v83
	v_mul_f32_e32 v83, 0xbfb8aa3b, v81
	v_rcp_f32_e32 v80, v80
	v_exp_f32_e32 v83, v83
	v_mul_f32_e32 v49, v156, v49
	s_waitcnt vmcnt(3)
	v_mul_f32_e32 v48, v108, v48
	v_mul_f32_e32 v80, v80, v82
	v_add_f32_e32 v82, 1.0, v83
	v_rcp_f32_e32 v82, v82
	v_mul_f32_e32 v50, v50, v80
	v_mul_f32_e32 v49, v109, v49
	v_mul_f32_e32 v50, v156, v50
	v_mul_f32_e32 v80, v82, v81
	v_mul_f32_e32 v51, v51, v80
	v_lshlrev_b32_e32 v80, 16, v116
	v_mul_f32_e32 v81, 0xbfb8aa3b, v80
	v_exp_f32_e32 v81, v81
	v_mul_f32_e32 v51, v156, v51
	v_mul_f32_e32 v50, v110, v50
	v_mul_f32_e32 v51, v111, v51
	v_cvt_pk_bf16_f32 v48, v48, v49
	v_cvt_pk_bf16_f32 v49, v50, v51
	v_mov_b64_e32 v[246:247], v[48:49]
	v_add_f32_e32 v48, 1.0, v81
	v_and_b32_e32 v49, 0xffff0000, v116
	v_rcp_f32_e32 v48, v48
	v_mul_f32_e32 v50, 0xbfb8aa3b, v49
	v_exp_f32_e32 v50, v50
	v_lshlrev_b32_e32 v51, 16, v117
	v_mul_f32_e32 v48, v48, v80
	v_mul_f32_e32 v48, v52, v48
	v_add_f32_e32 v50, 1.0, v50
	v_mul_f32_e32 v52, 0xbfb8aa3b, v51
	v_rcp_f32_e32 v50, v50
	v_exp_f32_e32 v52, v52
	v_mul_f32_e32 v48, v156, v48
	s_waitcnt vmcnt(2)
	v_mul_f32_e32 v48, v104, v48
	v_mul_f32_e32 v49, v50, v49
	v_add_f32_e32 v50, 1.0, v52
	v_and_b32_e32 v52, 0xffff0000, v117
	v_mul_f32_e32 v49, v53, v49
	v_mul_f32_e32 v53, 0xbfb8aa3b, v52
	v_rcp_f32_e32 v50, v50
	v_exp_f32_e32 v53, v53
	v_mul_f32_e32 v49, v156, v49
	v_mul_f32_e32 v49, v105, v49
	v_mul_f32_e32 v50, v50, v51
	v_add_f32_e32 v51, 1.0, v53
	v_rcp_f32_e32 v51, v51
	v_mul_f32_e32 v50, v54, v50
	v_mul_f32_e32 v50, v156, v50
	v_mul_f32_e32 v50, v106, v50
	v_mul_f32_e32 v51, v51, v52
	v_lshlrev_b32_e32 v52, 16, v114
	v_mul_f32_e32 v53, 0xbfb8aa3b, v52
	v_mul_f32_e32 v51, v55, v51
	v_exp_f32_e32 v53, v53
	v_mul_f32_e32 v51, v156, v51
	v_mul_f32_e32 v51, v107, v51
	v_cvt_pk_bf16_f32 v48, v48, v49
	v_cvt_pk_bf16_f32 v49, v50, v51
	v_mov_b64_e32 v[248:249], v[48:49]
	s_nop 1
	v_permlane32_swap_b32_e32 v246, v248
	v_permlane32_swap_b32_e32 v247, v249
	ds_write_b128 v206, v[246:249] offset:192
	v_and_b32_e32 v49, 0xffff0000, v114
	v_add_f32_e32 v48, 1.0, v53
	v_mul_f32_e32 v50, 0xbfb8aa3b, v49
	v_rcp_f32_e32 v48, v48
	v_exp_f32_e32 v50, v50
	v_lshlrev_b32_e32 v51, 16, v115
	v_mul_f32_e32 v48, v48, v52
	v_add_f32_e32 v50, 1.0, v50
	v_mul_f32_e32 v52, 0xbfb8aa3b, v51
	v_rcp_f32_e32 v50, v50
	v_exp_f32_e32 v52, v52
	v_mul_f32_e32 v48, v56, v48
	v_mul_f32_e32 v48, v156, v48
	v_mul_f32_e32 v49, v50, v49
	v_add_f32_e32 v50, 1.0, v52
	v_and_b32_e32 v52, 0xffff0000, v115
	v_mul_f32_e32 v53, 0xbfb8aa3b, v52
	v_rcp_f32_e32 v50, v50
	v_exp_f32_e32 v53, v53
	v_mul_f32_e32 v49, v57, v49
	v_mul_f32_e32 v49, v156, v49
	v_mul_f32_e32 v50, v50, v51
	v_add_f32_e32 v51, 1.0, v53
	v_rcp_f32_e32 v51, v51
	v_mul_f32_e32 v50, v58, v50
	s_waitcnt vmcnt(1)
	v_mul_f32_e32 v48, v100, v48
	v_mul_f32_e32 v49, v101, v49
	v_mul_f32_e32 v51, v51, v52
	v_lshlrev_b32_e32 v52, 16, v112
	v_mul_f32_e32 v53, 0xbfb8aa3b, v52
	v_mul_f32_e32 v51, v59, v51
	v_exp_f32_e32 v53, v53
	v_mul_f32_e32 v50, v156, v50
	v_mul_f32_e32 v51, v156, v51
	v_mul_f32_e32 v50, v102, v50
	v_mul_f32_e32 v51, v103, v51
	v_cvt_pk_bf16_f32 v48, v48, v49
	v_cvt_pk_bf16_f32 v49, v50, v51
	v_mov_b64_e32 v[230:231], v[48:49]
	v_and_b32_e32 v49, 0xffff0000, v112
	v_add_f32_e32 v48, 1.0, v53
	v_mul_f32_e32 v50, 0xbfb8aa3b, v49
	v_rcp_f32_e32 v48, v48
	v_exp_f32_e32 v50, v50
	v_lshlrev_b32_e32 v51, 16, v113
	v_mul_f32_e32 v48, v48, v52
	v_add_f32_e32 v50, 1.0, v50
	v_mul_f32_e32 v52, 0xbfb8aa3b, v51
	v_rcp_f32_e32 v50, v50
	v_exp_f32_e32 v52, v52
	v_mul_f32_e32 v48, v60, v48
	v_mul_f32_e32 v48, v156, v48
	v_mul_f32_e32 v49, v50, v49
	v_add_f32_e32 v50, 1.0, v52
	v_and_b32_e32 v52, 0xffff0000, v113
	v_mul_f32_e32 v53, 0xbfb8aa3b, v52
	v_rcp_f32_e32 v50, v50
	v_exp_f32_e32 v53, v53
	v_mul_f32_e32 v49, v61, v49
	v_mul_f32_e32 v49, v156, v49
	v_mul_f32_e32 v50, v50, v51
	v_add_f32_e32 v51, 1.0, v53
	v_rcp_f32_e32 v51, v51
	v_mul_f32_e32 v50, v62, v50
	s_waitcnt vmcnt(0)
	v_mul_f32_e32 v48, v96, v48
	v_mul_f32_e32 v49, v97, v49
	v_mul_f32_e32 v51, v51, v52
	v_mul_f32_e32 v51, v63, v51
	v_mul_f32_e32 v50, v156, v50
	v_mul_f32_e32 v51, v156, v51
	v_mul_f32_e32 v50, v98, v50
	v_mul_f32_e32 v51, v99, v51
	v_cvt_pk_bf16_f32 v48, v48, v49
	v_cvt_pk_bf16_f32 v49, v50, v51
	s_waitcnt lgkmcnt(7)
	v_permlane32_swap_b32_e32 v188, v190
	v_permlane32_swap_b32_e32 v189, v191
	s_waitcnt lgkmcnt(6)
	v_permlane32_swap_b32_e32 v192, v194
	v_permlane32_swap_b32_e32 v193, v195
	s_waitcnt lgkmcnt(5)
	v_permlane32_swap_b32_e32 v196, v198
	v_permlane32_swap_b32_e32 v197, v199
	s_waitcnt lgkmcnt(4)
	v_permlane32_swap_b32_e32 v202, v204
	v_permlane32_swap_b32_e32 v203, v205
	v_mov_b64_e32 v[104:105], v[188:189]
	v_mov_b64_e32 v[106:107], v[190:191]
	v_mov_b64_e32 v[108:109], v[192:193]
	v_mov_b64_e32 v[110:111], v[194:195]
	v_mov_b64_e32 v[86:87], v[196:197]
	v_mov_b64_e32 v[84:85], v[198:199]
	v_mov_b64_e32 v[82:83], v[202:203]
	v_mov_b64_e32 v[80:81], v[204:205]
	ds_read_b128 v[210:213], v206 offset:384
	ds_read_b128 v[216:219], v206 offset:416
	ds_read_b128 v[220:223], v206 offset:448
	ds_read_b128 v[224:227], v206 offset:480
	v_lshlrev_b32_e32 v112, 16, v104
	v_mov_b64_e32 v[232:233], v[48:49]
	s_nop 1
	v_permlane32_swap_b32_e32 v230, v232
	v_permlane32_swap_b32_e32 v231, v233
	ds_write_b128 v206, v[230:233] offset:224
	global_load_dwordx4 v[88:91], v[146:147], off offset:512
	global_load_dwordx4 v[92:95], v[146:147], off offset:544
	global_load_dwordx4 v[96:99], v[146:147], off offset:576
	global_load_dwordx4 v[100:103], v[146:147], off offset:608
	global_load_dwordx4 v[60:63], v[146:147], off offset:640
	global_load_dwordx4 v[56:59], v[146:147], off offset:672
	v_mul_f32_e32 v48, 0xbfb8aa3b, v112
	v_exp_f32_e32 v113, v48
	v_and_b32_e32 v104, 0xffff0000, v104
	v_mul_f32_e32 v114, 0xbfb8aa3b, v104
	v_exp_f32_e32 v114, v114
	v_add_f32_e32 v113, 1.0, v113
	v_rcp_f32_e32 v113, v113
	global_load_dwordx4 v[52:55], v[146:147], off offset:704
	global_load_dwordx4 v[48:51], v[146:147], off offset:736
	v_mul_f32_e32 v112, v113, v112
	v_mul_f32_e32 v64, v64, v112
	v_add_f32_e32 v112, 1.0, v114
	v_rcp_f32_e32 v112, v112
	v_mul_f32_e32 v64, v156, v64
	v_lshlrev_b32_e32 v113, 16, v105
	v_mul_f32_e32 v114, 0xbfb8aa3b, v113
	v_exp_f32_e32 v114, v114
	s_waitcnt vmcnt(7)
	v_mul_f32_e32 v64, v88, v64
	v_mul_f32_e32 v88, v112, v104
	v_and_b32_e32 v104, 0xffff0000, v105
	v_mul_f32_e32 v105, 0xbfb8aa3b, v104
	v_exp_f32_e32 v105, v105
	v_mul_f32_e32 v65, v65, v88
	v_add_f32_e32 v88, 1.0, v114
	v_mul_f32_e32 v65, v156, v65
	v_rcp_f32_e32 v88, v88
	v_mul_f32_e32 v65, v89, v65
	v_add_f32_e32 v89, 1.0, v105
	v_rcp_f32_e32 v89, v89
	v_mul_f32_e32 v88, v88, v113
	v_mul_f32_e32 v66, v66, v88
	v_mul_f32_e32 v66, v156, v66
	v_mul_f32_e32 v88, v89, v104
	v_mul_f32_e32 v67, v67, v88
	v_lshlrev_b32_e32 v88, 16, v106
	v_mul_f32_e32 v89, 0xbfb8aa3b, v88
	v_exp_f32_e32 v89, v89
	v_mul_f32_e32 v67, v156, v67
	v_mul_f32_e32 v66, v90, v66
	v_mul_f32_e32 v67, v91, v67
	v_cvt_pk_bf16_f32 v64, v64, v65
	v_cvt_pk_bf16_f32 v65, v66, v67
	v_mov_b64_e32 v[238:239], v[64:65]
	v_add_f32_e32 v64, 1.0, v89
	v_and_b32_e32 v65, 0xffff0000, v106
	v_rcp_f32_e32 v64, v64
	v_mul_f32_e32 v66, 0xbfb8aa3b, v65
	v_exp_f32_e32 v66, v66
	v_lshlrev_b32_e32 v67, 16, v107
	v_mul_f32_e32 v64, v64, v88
	v_mul_f32_e32 v64, v68, v64
	v_add_f32_e32 v66, 1.0, v66
	v_mul_f32_e32 v68, 0xbfb8aa3b, v67
	v_rcp_f32_e32 v66, v66
	v_exp_f32_e32 v68, v68
	v_mul_f32_e32 v64, v156, v64
	s_waitcnt vmcnt(6)
	v_mul_f32_e32 v64, v92, v64
	v_mul_f32_e32 v65, v66, v65
	v_add_f32_e32 v66, 1.0, v68
	v_and_b32_e32 v68, 0xffff0000, v107
	v_mul_f32_e32 v65, v69, v65
	v_mul_f32_e32 v69, 0xbfb8aa3b, v68
	v_rcp_f32_e32 v66, v66
	v_exp_f32_e32 v69, v69
	v_mul_f32_e32 v65, v156, v65
	v_mul_f32_e32 v65, v93, v65
	v_mul_f32_e32 v66, v66, v67
	v_add_f32_e32 v67, 1.0, v69
	v_rcp_f32_e32 v67, v67
	v_mul_f32_e32 v66, v70, v66
	v_mul_f32_e32 v66, v156, v66
	v_mul_f32_e32 v66, v94, v66
	v_mul_f32_e32 v67, v67, v68
	v_lshlrev_b32_e32 v68, 16, v108
	v_mul_f32_e32 v69, 0xbfb8aa3b, v68
	v_mul_f32_e32 v67, v71, v67
	v_exp_f32_e32 v69, v69
	v_mul_f32_e32 v67, v156, v67
	v_mul_f32_e32 v67, v95, v67
	v_cvt_pk_bf16_f32 v64, v64, v65
	v_cvt_pk_bf16_f32 v65, v66, v67
	v_mov_b64_e32 v[240:241], v[64:65]
	s_nop 1
	v_permlane32_swap_b32_e32 v238, v240
	v_permlane32_swap_b32_e32 v239, v241
	ds_write_b128 v206, v[238:241] offset:256
	v_and_b32_e32 v65, 0xffff0000, v108
	v_add_f32_e32 v64, 1.0, v69
	v_mul_f32_e32 v66, 0xbfb8aa3b, v65
	v_rcp_f32_e32 v64, v64
	v_exp_f32_e32 v66, v66
	v_lshlrev_b32_e32 v67, 16, v109
	v_mul_f32_e32 v64, v64, v68
	v_add_f32_e32 v66, 1.0, v66
	v_mul_f32_e32 v68, 0xbfb8aa3b, v67
	v_rcp_f32_e32 v66, v66
	v_exp_f32_e32 v68, v68
	v_mul_f32_e32 v64, v72, v64
	v_mul_f32_e32 v64, v156, v64
	v_mul_f32_e32 v65, v66, v65
	v_add_f32_e32 v66, 1.0, v68
	v_and_b32_e32 v68, 0xffff0000, v109
	v_mul_f32_e32 v69, 0xbfb8aa3b, v68
	v_rcp_f32_e32 v66, v66
	v_exp_f32_e32 v69, v69
	v_mul_f32_e32 v65, v73, v65
	v_mul_f32_e32 v65, v156, v65
	v_mul_f32_e32 v66, v66, v67
	v_add_f32_e32 v67, 1.0, v69
	v_rcp_f32_e32 v67, v67
	v_mul_f32_e32 v66, v74, v66
	s_waitcnt vmcnt(5)
	v_mul_f32_e32 v64, v96, v64
	v_mul_f32_e32 v65, v97, v65
	v_mul_f32_e32 v67, v67, v68
	v_lshlrev_b32_e32 v68, 16, v110
	v_mul_f32_e32 v69, 0xbfb8aa3b, v68
	v_mul_f32_e32 v67, v75, v67
	v_exp_f32_e32 v69, v69
	v_mul_f32_e32 v66, v156, v66
	v_mul_f32_e32 v67, v156, v67
	v_mul_f32_e32 v66, v98, v66
	v_mul_f32_e32 v67, v99, v67
	v_cvt_pk_bf16_f32 v64, v64, v65
	v_cvt_pk_bf16_f32 v65, v66, v67
	v_mov_b64_e32 v[242:243], v[64:65]
	v_and_b32_e32 v65, 0xffff0000, v110
	v_add_f32_e32 v64, 1.0, v69
	v_mul_f32_e32 v66, 0xbfb8aa3b, v65
	v_rcp_f32_e32 v64, v64
	v_exp_f32_e32 v66, v66
	v_lshlrev_b32_e32 v67, 16, v111
	v_mul_f32_e32 v64, v64, v68
	v_add_f32_e32 v66, 1.0, v66
	v_mul_f32_e32 v68, 0xbfb8aa3b, v67
	v_rcp_f32_e32 v66, v66
	v_exp_f32_e32 v68, v68
	v_mul_f32_e32 v64, v76, v64
	v_mul_f32_e32 v64, v156, v64
	v_mul_f32_e32 v65, v66, v65
	v_add_f32_e32 v66, 1.0, v68
	v_and_b32_e32 v68, 0xffff0000, v111
	v_mul_f32_e32 v69, 0xbfb8aa3b, v68
	v_rcp_f32_e32 v66, v66
	v_exp_f32_e32 v69, v69
	v_mul_f32_e32 v65, v77, v65
	v_mul_f32_e32 v65, v156, v65
	v_mul_f32_e32 v66, v66, v67
	v_add_f32_e32 v67, 1.0, v69
	v_rcp_f32_e32 v67, v67
	v_mul_f32_e32 v66, v78, v66
	s_waitcnt vmcnt(4)
	v_mul_f32_e32 v64, v100, v64
	v_mul_f32_e32 v65, v101, v65
	v_mul_f32_e32 v67, v67, v68
	v_lshlrev_b32_e32 v68, 16, v86
	v_mul_f32_e32 v69, 0xbfb8aa3b, v68
	v_exp_f32_e32 v69, v69
	v_mul_f32_e32 v67, v79, v67
	v_mul_f32_e32 v66, v156, v66
	v_mul_f32_e32 v67, v156, v67
	v_mul_f32_e32 v66, v102, v66
	v_mul_f32_e32 v67, v103, v67
	v_cvt_pk_bf16_f32 v64, v64, v65
	v_cvt_pk_bf16_f32 v65, v66, v67
	v_mov_b64_e32 v[244:245], v[64:65]
	s_nop 1
	v_permlane32_swap_b32_e32 v242, v244
	v_permlane32_swap_b32_e32 v243, v245
	ds_write_b128 v206, v[242:245] offset:288
	v_add_f32_e32 v64, 1.0, v69
	v_and_b32_e32 v65, 0xffff0000, v86
	v_rcp_f32_e32 v64, v64
	v_mul_f32_e32 v66, 0xbfb8aa3b, v65
	v_exp_f32_e32 v66, v66
	v_mul_f32_e32 v64, v64, v68
	v_mul_f32_e32 v32, v32, v64
	v_add_f32_e32 v64, 1.0, v66
	v_rcp_f32_e32 v64, v64
	v_mul_f32_e32 v32, v156, v32
	v_lshlrev_b32_e32 v66, 16, v87
	v_mul_f32_e32 v67, 0xbfb8aa3b, v66
	s_waitcnt vmcnt(3)
	v_mul_f32_e32 v32, v60, v32
	v_mul_f32_e32 v60, v64, v65
	v_and_b32_e32 v64, 0xffff0000, v87
	v_exp_f32_e32 v67, v67
	v_mul_f32_e32 v65, 0xbfb8aa3b, v64
	v_exp_f32_e32 v65, v65
	v_mul_f32_e32 v33, v33, v60
	v_add_f32_e32 v60, 1.0, v67
	v_mul_f32_e32 v33, v156, v33
	v_rcp_f32_e32 v60, v60
	v_mul_f32_e32 v33, v61, v33
	v_add_f32_e32 v61, 1.0, v65
	v_rcp_f32_e32 v61, v61
	v_mul_f32_e32 v60, v60, v66
	v_mul_f32_e32 v34, v34, v60
	v_mul_f32_e32 v34, v156, v34
	v_mul_f32_e32 v60, v61, v64
	v_mul_f32_e32 v35, v35, v60
	v_lshlrev_b32_e32 v60, 16, v84
	v_mul_f32_e32 v61, 0xbfb8aa3b, v60
	v_exp_f32_e32 v61, v61
	v_mul_f32_e32 v35, v156, v35
	v_mul_f32_e32 v34, v62, v34
	v_mul_f32_e32 v35, v63, v35
	v_cvt_pk_bf16_f32 v32, v32, v33
	v_cvt_pk_bf16_f32 v33, v34, v35
	v_mov_b64_e32 v[246:247], v[32:33]
	v_add_f32_e32 v32, 1.0, v61
	v_and_b32_e32 v33, 0xffff0000, v84
	v_rcp_f32_e32 v32, v32
	v_mul_f32_e32 v34, 0xbfb8aa3b, v33
	v_exp_f32_e32 v34, v34
	v_lshlrev_b32_e32 v35, 16, v85
	v_mul_f32_e32 v32, v32, v60
	v_mul_f32_e32 v32, v36, v32
	v_add_f32_e32 v34, 1.0, v34
	v_mul_f32_e32 v36, 0xbfb8aa3b, v35
	v_rcp_f32_e32 v34, v34
	v_exp_f32_e32 v36, v36
	v_mul_f32_e32 v32, v156, v32
	s_waitcnt vmcnt(2)
	v_mul_f32_e32 v32, v56, v32
	v_mul_f32_e32 v33, v34, v33
	v_add_f32_e32 v34, 1.0, v36
	v_and_b32_e32 v36, 0xffff0000, v85
	v_mul_f32_e32 v33, v37, v33
	v_mul_f32_e32 v37, 0xbfb8aa3b, v36
	v_rcp_f32_e32 v34, v34
	v_exp_f32_e32 v37, v37
	v_mul_f32_e32 v33, v156, v33
	v_mul_f32_e32 v33, v57, v33
	v_mul_f32_e32 v34, v34, v35
	v_add_f32_e32 v35, 1.0, v37
	v_rcp_f32_e32 v35, v35
	v_mul_f32_e32 v34, v38, v34
	v_mul_f32_e32 v34, v156, v34
	v_mul_f32_e32 v34, v58, v34
	v_mul_f32_e32 v35, v35, v36
	v_lshlrev_b32_e32 v36, 16, v82
	v_mul_f32_e32 v37, 0xbfb8aa3b, v36
	v_mul_f32_e32 v35, v39, v35
	v_exp_f32_e32 v37, v37
	v_mul_f32_e32 v35, v156, v35
	v_mul_f32_e32 v35, v59, v35
	v_cvt_pk_bf16_f32 v32, v32, v33
	v_cvt_pk_bf16_f32 v33, v34, v35
	v_mov_b64_e32 v[248:249], v[32:33]
	s_nop 1
	v_permlane32_swap_b32_e32 v246, v248
	v_permlane32_swap_b32_e32 v247, v249
	ds_write_b128 v206, v[246:249] offset:320
	v_and_b32_e32 v33, 0xffff0000, v82
	v_add_f32_e32 v32, 1.0, v37
	v_mul_f32_e32 v34, 0xbfb8aa3b, v33
	v_rcp_f32_e32 v32, v32
	v_exp_f32_e32 v34, v34
	v_lshlrev_b32_e32 v35, 16, v83
	v_mul_f32_e32 v32, v32, v36
	v_add_f32_e32 v34, 1.0, v34
	v_mul_f32_e32 v36, 0xbfb8aa3b, v35
	v_rcp_f32_e32 v34, v34
	v_exp_f32_e32 v36, v36
	v_mul_f32_e32 v32, v40, v32
	v_mul_f32_e32 v32, v156, v32
	v_mul_f32_e32 v33, v34, v33
	v_add_f32_e32 v34, 1.0, v36
	v_and_b32_e32 v36, 0xffff0000, v83
	v_mul_f32_e32 v37, 0xbfb8aa3b, v36
	v_rcp_f32_e32 v34, v34
	v_exp_f32_e32 v37, v37
	v_mul_f32_e32 v33, v41, v33
	v_mul_f32_e32 v33, v156, v33
	v_mul_f32_e32 v34, v34, v35
	v_add_f32_e32 v35, 1.0, v37
	v_rcp_f32_e32 v35, v35
	v_mul_f32_e32 v34, v42, v34
	s_waitcnt vmcnt(1)
	v_mul_f32_e32 v32, v52, v32
	v_mul_f32_e32 v33, v53, v33
	v_mul_f32_e32 v35, v35, v36
	v_lshlrev_b32_e32 v36, 16, v80
	v_mul_f32_e32 v37, 0xbfb8aa3b, v36
	v_mul_f32_e32 v35, v43, v35
	v_exp_f32_e32 v37, v37
	v_mul_f32_e32 v34, v156, v34
	v_mul_f32_e32 v35, v156, v35
	v_mul_f32_e32 v34, v54, v34
	v_mul_f32_e32 v35, v55, v35
	v_cvt_pk_bf16_f32 v32, v32, v33
	v_cvt_pk_bf16_f32 v33, v34, v35
	v_mov_b64_e32 v[230:231], v[32:33]
	v_and_b32_e32 v33, 0xffff0000, v80
	v_add_f32_e32 v32, 1.0, v37
	v_mul_f32_e32 v34, 0xbfb8aa3b, v33
	v_rcp_f32_e32 v32, v32
	v_exp_f32_e32 v34, v34
	v_lshlrev_b32_e32 v35, 16, v81
	v_mul_f32_e32 v32, v32, v36
	v_add_f32_e32 v34, 1.0, v34
	v_mul_f32_e32 v36, 0xbfb8aa3b, v35
	v_rcp_f32_e32 v34, v34
	v_exp_f32_e32 v36, v36
	v_mul_f32_e32 v32, v44, v32
	v_mul_f32_e32 v32, v156, v32
	v_mul_f32_e32 v33, v34, v33
	v_add_f32_e32 v34, 1.0, v36
	v_and_b32_e32 v36, 0xffff0000, v81
	v_mul_f32_e32 v37, 0xbfb8aa3b, v36
	v_rcp_f32_e32 v34, v34
	v_exp_f32_e32 v37, v37
	v_mul_f32_e32 v33, v45, v33
	v_mul_f32_e32 v33, v156, v33
	v_mul_f32_e32 v34, v34, v35
	v_add_f32_e32 v35, 1.0, v37
	v_rcp_f32_e32 v35, v35
	v_mul_f32_e32 v34, v46, v34
	s_waitcnt vmcnt(0)
	v_mul_f32_e32 v32, v48, v32
	v_mul_f32_e32 v33, v49, v33
	v_mul_f32_e32 v35, v35, v36
	v_mul_f32_e32 v35, v47, v35
	v_mul_f32_e32 v34, v156, v34
	v_mul_f32_e32 v35, v156, v35
	v_mul_f32_e32 v34, v50, v34
	v_mul_f32_e32 v35, v51, v35
	v_cvt_pk_bf16_f32 v32, v32, v33
	v_cvt_pk_bf16_f32 v33, v34, v35
	s_waitcnt lgkmcnt(7)
	v_permlane32_swap_b32_e32 v210, v212
	v_permlane32_swap_b32_e32 v211, v213
	s_waitcnt lgkmcnt(6)
	v_permlane32_swap_b32_e32 v216, v218
	v_permlane32_swap_b32_e32 v217, v219
	s_waitcnt lgkmcnt(5)
	v_permlane32_swap_b32_e32 v220, v222
	v_permlane32_swap_b32_e32 v221, v223
	s_waitcnt lgkmcnt(4)
	v_permlane32_swap_b32_e32 v224, v226
	v_permlane32_swap_b32_e32 v225, v227
	v_mov_b64_e32 v[72:73], v[210:211]
	v_mov_b64_e32 v[74:75], v[212:213]
	v_mov_b64_e32 v[76:77], v[216:217]
	v_mov_b64_e32 v[78:79], v[218:219]
	v_mov_b64_e32 v[54:55], v[220:221]
	v_mov_b64_e32 v[52:53], v[222:223]
	v_mov_b64_e32 v[50:51], v[224:225]
	v_mov_b64_e32 v[48:49], v[226:227]
	v_lshlrev_b32_e32 v80, 16, v72
	v_mov_b64_e32 v[232:233], v[32:33]
	s_nop 1
	v_permlane32_swap_b32_e32 v230, v232
	v_permlane32_swap_b32_e32 v231, v233
	ds_write_b128 v206, v[230:233] offset:352
	global_load_dwordx4 v[56:59], v[146:147], off offset:768
	global_load_dwordx4 v[60:63], v[146:147], off offset:800
	global_load_dwordx4 v[64:67], v[146:147], off offset:832
	global_load_dwordx4 v[68:71], v[146:147], off offset:864
	global_load_dwordx4 v[44:47], v[146:147], off offset:896
	global_load_dwordx4 v[40:43], v[146:147], off offset:928
	v_mul_f32_e32 v32, 0xbfb8aa3b, v80
	v_exp_f32_e32 v81, v32
	v_and_b32_e32 v72, 0xffff0000, v72
	v_mul_f32_e32 v82, 0xbfb8aa3b, v72
	v_exp_f32_e32 v82, v82
	v_add_f32_e32 v81, 1.0, v81
	v_rcp_f32_e32 v81, v81
	global_load_dwordx4 v[36:39], v[146:147], off offset:960
	global_load_dwordx4 v[32:35], v[146:147], off offset:992
	v_mul_f32_e32 v80, v81, v80
	v_mul_f32_e32 v16, v16, v80
	v_add_f32_e32 v80, 1.0, v82
	v_rcp_f32_e32 v80, v80
	v_mul_f32_e32 v16, v156, v16
	v_lshlrev_b32_e32 v81, 16, v73
	v_mul_f32_e32 v82, 0xbfb8aa3b, v81
	v_exp_f32_e32 v82, v82
	s_waitcnt vmcnt(7)
	v_mul_f32_e32 v16, v56, v16
	v_mul_f32_e32 v56, v80, v72
	v_and_b32_e32 v72, 0xffff0000, v73
	v_mul_f32_e32 v73, 0xbfb8aa3b, v72
	v_exp_f32_e32 v73, v73
	v_mul_f32_e32 v17, v17, v56
	v_add_f32_e32 v56, 1.0, v82
	v_mul_f32_e32 v17, v156, v17
	v_rcp_f32_e32 v56, v56
	v_mul_f32_e32 v17, v57, v17
	v_add_f32_e32 v57, 1.0, v73
	v_rcp_f32_e32 v57, v57
	v_mul_f32_e32 v56, v56, v81
	v_mul_f32_e32 v18, v18, v56
	v_mul_f32_e32 v18, v156, v18
	v_mul_f32_e32 v56, v57, v72
	v_mul_f32_e32 v19, v19, v56
	v_lshlrev_b32_e32 v56, 16, v74
	v_mul_f32_e32 v57, 0xbfb8aa3b, v56
	v_exp_f32_e32 v57, v57
	v_mul_f32_e32 v19, v156, v19
	v_mul_f32_e32 v18, v58, v18
	v_mul_f32_e32 v19, v59, v19
	v_cvt_pk_bf16_f32 v16, v16, v17
	v_cvt_pk_bf16_f32 v17, v18, v19
	v_mov_b64_e32 v[238:239], v[16:17]
	v_add_f32_e32 v16, 1.0, v57
	v_and_b32_e32 v17, 0xffff0000, v74
	v_rcp_f32_e32 v16, v16
	v_mul_f32_e32 v18, 0xbfb8aa3b, v17
	v_exp_f32_e32 v18, v18
	v_lshlrev_b32_e32 v19, 16, v75
	v_mul_f32_e32 v16, v16, v56
	v_mul_f32_e32 v16, v20, v16
	v_add_f32_e32 v18, 1.0, v18
	v_mul_f32_e32 v20, 0xbfb8aa3b, v19
	v_rcp_f32_e32 v18, v18
	v_exp_f32_e32 v20, v20
	v_mul_f32_e32 v16, v156, v16
	s_waitcnt vmcnt(6)
	v_mul_f32_e32 v16, v60, v16
	v_mul_f32_e32 v17, v18, v17
	v_add_f32_e32 v18, 1.0, v20
	v_and_b32_e32 v20, 0xffff0000, v75
	v_mul_f32_e32 v17, v21, v17
	v_mul_f32_e32 v21, 0xbfb8aa3b, v20
	v_rcp_f32_e32 v18, v18
	v_exp_f32_e32 v21, v21
	v_mul_f32_e32 v17, v156, v17
	v_mul_f32_e32 v17, v61, v17
	v_mul_f32_e32 v18, v18, v19
	v_add_f32_e32 v19, 1.0, v21
	v_rcp_f32_e32 v19, v19
	v_mul_f32_e32 v18, v22, v18
	v_mul_f32_e32 v18, v156, v18
	v_mul_f32_e32 v18, v62, v18
	v_mul_f32_e32 v19, v19, v20
	v_lshlrev_b32_e32 v20, 16, v76
	v_mul_f32_e32 v21, 0xbfb8aa3b, v20
	v_mul_f32_e32 v19, v23, v19
	v_exp_f32_e32 v21, v21
	v_mul_f32_e32 v19, v156, v19
	v_mul_f32_e32 v19, v63, v19
	v_cvt_pk_bf16_f32 v16, v16, v17
	v_cvt_pk_bf16_f32 v17, v18, v19
	v_mov_b64_e32 v[240:241], v[16:17]
	s_nop 1
	v_permlane32_swap_b32_e32 v238, v240
	v_permlane32_swap_b32_e32 v239, v241
	ds_write_b128 v206, v[238:241] offset:384
	v_and_b32_e32 v17, 0xffff0000, v76
	v_add_f32_e32 v16, 1.0, v21
	v_mul_f32_e32 v18, 0xbfb8aa3b, v17
	v_rcp_f32_e32 v16, v16
	v_exp_f32_e32 v18, v18
	v_lshlrev_b32_e32 v19, 16, v77
	v_mul_f32_e32 v16, v16, v20
	v_add_f32_e32 v18, 1.0, v18
	v_mul_f32_e32 v20, 0xbfb8aa3b, v19
	v_rcp_f32_e32 v18, v18
	v_exp_f32_e32 v20, v20
	v_mul_f32_e32 v16, v24, v16
	v_mul_f32_e32 v16, v156, v16
	v_mul_f32_e32 v17, v18, v17
	v_add_f32_e32 v18, 1.0, v20
	v_and_b32_e32 v20, 0xffff0000, v77
	v_mul_f32_e32 v21, 0xbfb8aa3b, v20
	v_rcp_f32_e32 v18, v18
	v_exp_f32_e32 v21, v21
	v_mul_f32_e32 v17, v25, v17
	v_mul_f32_e32 v17, v156, v17
	v_mul_f32_e32 v18, v18, v19
	v_add_f32_e32 v19, 1.0, v21
	v_rcp_f32_e32 v19, v19
	v_mul_f32_e32 v18, v26, v18
	s_waitcnt vmcnt(5)
	v_mul_f32_e32 v16, v64, v16
	v_mul_f32_e32 v17, v65, v17
	v_mul_f32_e32 v19, v19, v20
	v_lshlrev_b32_e32 v20, 16, v78
	v_mul_f32_e32 v21, 0xbfb8aa3b, v20
	v_mul_f32_e32 v19, v27, v19
	v_exp_f32_e32 v21, v21
	v_mul_f32_e32 v18, v156, v18
	v_mul_f32_e32 v19, v156, v19
	v_mul_f32_e32 v18, v66, v18
	v_mul_f32_e32 v19, v67, v19
	v_cvt_pk_bf16_f32 v16, v16, v17
	v_cvt_pk_bf16_f32 v17, v18, v19
	v_mov_b64_e32 v[242:243], v[16:17]
	v_and_b32_e32 v17, 0xffff0000, v78
	v_add_f32_e32 v16, 1.0, v21
	v_mul_f32_e32 v18, 0xbfb8aa3b, v17
	v_rcp_f32_e32 v16, v16
	v_exp_f32_e32 v18, v18
	v_lshlrev_b32_e32 v19, 16, v79
	v_mul_f32_e32 v16, v16, v20
	v_add_f32_e32 v18, 1.0, v18
	v_mul_f32_e32 v20, 0xbfb8aa3b, v19
	v_rcp_f32_e32 v18, v18
	v_exp_f32_e32 v20, v20
	v_mul_f32_e32 v16, v28, v16
	v_mul_f32_e32 v16, v156, v16
	v_mul_f32_e32 v17, v18, v17
	v_add_f32_e32 v18, 1.0, v20
	v_and_b32_e32 v20, 0xffff0000, v79
	v_mul_f32_e32 v21, 0xbfb8aa3b, v20
	v_rcp_f32_e32 v18, v18
	v_exp_f32_e32 v21, v21
	v_mul_f32_e32 v17, v29, v17
	v_mul_f32_e32 v17, v156, v17
	v_mul_f32_e32 v18, v18, v19
	v_add_f32_e32 v19, 1.0, v21
	v_rcp_f32_e32 v19, v19
	v_mul_f32_e32 v18, v30, v18
	s_waitcnt vmcnt(4)
	v_mul_f32_e32 v16, v68, v16
	v_mul_f32_e32 v17, v69, v17
	v_mul_f32_e32 v19, v19, v20
	v_lshlrev_b32_e32 v20, 16, v54
	v_mul_f32_e32 v21, 0xbfb8aa3b, v20
	v_exp_f32_e32 v21, v21
	v_mul_f32_e32 v19, v31, v19
	v_mul_f32_e32 v18, v156, v18
	v_mul_f32_e32 v19, v156, v19
	v_mul_f32_e32 v18, v70, v18
	v_mul_f32_e32 v19, v71, v19
	v_cvt_pk_bf16_f32 v16, v16, v17
	v_cvt_pk_bf16_f32 v17, v18, v19
	v_mov_b64_e32 v[244:245], v[16:17]
	s_nop 1
	v_permlane32_swap_b32_e32 v242, v244
	v_permlane32_swap_b32_e32 v243, v245
	ds_write_b128 v206, v[242:245] offset:416
	v_add_f32_e32 v16, 1.0, v21
	v_and_b32_e32 v17, 0xffff0000, v54
	v_rcp_f32_e32 v16, v16
	v_mul_f32_e32 v18, 0xbfb8aa3b, v17
	v_exp_f32_e32 v18, v18
	v_mul_f32_e32 v16, v16, v20
	v_mul_f32_e32 v0, v0, v16
	v_add_f32_e32 v16, 1.0, v18
	v_lshlrev_b32_e32 v18, 16, v55
	v_rcp_f32_e32 v16, v16
	v_mul_f32_e32 v19, 0xbfb8aa3b, v18
	v_exp_f32_e32 v19, v19
	v_mul_f32_e32 v0, v156, v0
	v_mul_f32_e32 v16, v16, v17
	v_and_b32_e32 v17, 0xffff0000, v55
	v_mul_f32_e32 v1, v1, v16
	v_add_f32_e32 v16, 1.0, v19
	v_mul_f32_e32 v19, 0xbfb8aa3b, v17
	v_rcp_f32_e32 v16, v16
	v_exp_f32_e32 v19, v19
	v_mul_f32_e32 v1, v156, v1
	s_waitcnt vmcnt(3)
	v_mul_f32_e32 v0, v44, v0
	v_mul_f32_e32 v16, v16, v18
	v_add_f32_e32 v18, 1.0, v19
	v_rcp_f32_e32 v18, v18
	v_mul_f32_e32 v2, v2, v16
	v_mul_f32_e32 v1, v45, v1
	v_mul_f32_e32 v2, v156, v2
	v_mul_f32_e32 v16, v18, v17
	v_mul_f32_e32 v3, v3, v16
	v_lshlrev_b32_e32 v16, 16, v52
	v_mul_f32_e32 v17, 0xbfb8aa3b, v16
	v_exp_f32_e32 v17, v17
	v_mul_f32_e32 v3, v156, v3
	v_mul_f32_e32 v2, v46, v2
	v_mul_f32_e32 v3, v47, v3
	v_cvt_pk_bf16_f32 v0, v0, v1
	v_cvt_pk_bf16_f32 v1, v2, v3
	v_mov_b64_e32 v[246:247], v[0:1]
	v_add_f32_e32 v0, 1.0, v17
	v_and_b32_e32 v1, 0xffff0000, v52
	v_rcp_f32_e32 v0, v0
	v_mul_f32_e32 v2, 0xbfb8aa3b, v1
	v_exp_f32_e32 v2, v2
	v_lshlrev_b32_e32 v3, 16, v53
	v_mul_f32_e32 v0, v0, v16
	v_mul_f32_e32 v0, v4, v0
	v_add_f32_e32 v2, 1.0, v2
	v_mul_f32_e32 v4, 0xbfb8aa3b, v3
	v_rcp_f32_e32 v2, v2
	v_exp_f32_e32 v4, v4
	v_mul_f32_e32 v0, v156, v0
	s_waitcnt vmcnt(2)
	v_mul_f32_e32 v0, v40, v0
	v_mul_f32_e32 v1, v2, v1
	v_add_f32_e32 v2, 1.0, v4
	v_and_b32_e32 v4, 0xffff0000, v53
	v_mul_f32_e32 v1, v5, v1
	v_mul_f32_e32 v5, 0xbfb8aa3b, v4
	v_rcp_f32_e32 v2, v2
	v_exp_f32_e32 v5, v5
	v_mul_f32_e32 v1, v156, v1
	v_mul_f32_e32 v1, v41, v1
	v_mul_f32_e32 v2, v2, v3
	v_add_f32_e32 v3, 1.0, v5
	v_rcp_f32_e32 v3, v3
	v_mul_f32_e32 v2, v6, v2
	v_mul_f32_e32 v2, v156, v2
	v_mul_f32_e32 v2, v42, v2
	v_mul_f32_e32 v3, v3, v4
	v_lshlrev_b32_e32 v4, 16, v50
	v_mul_f32_e32 v5, 0xbfb8aa3b, v4
	v_mul_f32_e32 v3, v7, v3
	v_exp_f32_e32 v5, v5
	v_mul_f32_e32 v3, v156, v3
	v_mul_f32_e32 v3, v43, v3
	v_cvt_pk_bf16_f32 v0, v0, v1
	v_cvt_pk_bf16_f32 v1, v2, v3
	v_mov_b64_e32 v[248:249], v[0:1]
	s_nop 1
	v_permlane32_swap_b32_e32 v246, v248
	v_permlane32_swap_b32_e32 v247, v249
	ds_write_b128 v206, v[246:249] offset:448
	v_and_b32_e32 v1, 0xffff0000, v50
	v_add_f32_e32 v0, 1.0, v5
	v_mul_f32_e32 v2, 0xbfb8aa3b, v1
	v_rcp_f32_e32 v0, v0
	v_exp_f32_e32 v2, v2
	v_lshlrev_b32_e32 v3, 16, v51
	v_mul_f32_e32 v0, v0, v4
	v_add_f32_e32 v2, 1.0, v2
	v_mul_f32_e32 v4, 0xbfb8aa3b, v3
	v_rcp_f32_e32 v2, v2
	v_exp_f32_e32 v4, v4
	v_mul_f32_e32 v0, v8, v0
	v_mul_f32_e32 v0, v156, v0
	v_mul_f32_e32 v1, v2, v1
	v_add_f32_e32 v2, 1.0, v4
	v_and_b32_e32 v4, 0xffff0000, v51
	v_mul_f32_e32 v5, 0xbfb8aa3b, v4
	v_rcp_f32_e32 v2, v2
	v_exp_f32_e32 v5, v5
	v_mul_f32_e32 v1, v9, v1
	v_mul_f32_e32 v1, v156, v1
	v_mul_f32_e32 v2, v2, v3
	v_add_f32_e32 v3, 1.0, v5
	v_rcp_f32_e32 v3, v3
	v_mul_f32_e32 v2, v10, v2
	s_waitcnt vmcnt(1)
	v_mul_f32_e32 v0, v36, v0
	v_mul_f32_e32 v1, v37, v1
	v_mul_f32_e32 v3, v3, v4
	v_lshlrev_b32_e32 v4, 16, v48
	v_mul_f32_e32 v5, 0xbfb8aa3b, v4
	v_mul_f32_e32 v3, v11, v3
	v_exp_f32_e32 v5, v5
	v_mul_f32_e32 v2, v156, v2
	v_mul_f32_e32 v3, v156, v3
	v_mul_f32_e32 v2, v38, v2
	v_mul_f32_e32 v3, v39, v3
	v_cvt_pk_bf16_f32 v0, v0, v1
	v_cvt_pk_bf16_f32 v1, v2, v3
	v_mov_b64_e32 v[230:231], v[0:1]
	v_and_b32_e32 v1, 0xffff0000, v48
	v_add_f32_e32 v0, 1.0, v5
	v_mul_f32_e32 v2, 0xbfb8aa3b, v1
	v_rcp_f32_e32 v0, v0
	v_exp_f32_e32 v2, v2
	v_lshlrev_b32_e32 v3, 16, v49
	v_mul_f32_e32 v0, v0, v4
	v_add_f32_e32 v2, 1.0, v2
	v_mul_f32_e32 v4, 0xbfb8aa3b, v3
	v_rcp_f32_e32 v2, v2
	v_exp_f32_e32 v4, v4
	v_mul_f32_e32 v0, v12, v0
	v_mul_f32_e32 v0, v156, v0
	v_mul_f32_e32 v1, v2, v1
	v_add_f32_e32 v2, 1.0, v4
	v_and_b32_e32 v4, 0xffff0000, v49
	v_mul_f32_e32 v5, 0xbfb8aa3b, v4
	v_rcp_f32_e32 v2, v2
	v_exp_f32_e32 v5, v5
	v_mul_f32_e32 v1, v13, v1
	v_mul_f32_e32 v1, v156, v1
	v_mul_f32_e32 v2, v2, v3
	v_add_f32_e32 v3, 1.0, v5
	v_rcp_f32_e32 v3, v3
	v_mul_f32_e32 v2, v14, v2
	s_waitcnt vmcnt(0)
	v_mul_f32_e32 v0, v32, v0
	v_mul_f32_e32 v1, v33, v1
	v_mul_f32_e32 v3, v3, v4
	v_mul_f32_e32 v3, v15, v3
	v_mul_f32_e32 v2, v156, v2
	v_mul_f32_e32 v3, v156, v3
	v_mul_f32_e32 v2, v34, v2
	v_mul_f32_e32 v3, v35, v3
	v_cvt_pk_bf16_f32 v0, v0, v1
	v_cvt_pk_bf16_f32 v1, v2, v3
	v_mov_b64_e32 v[232:233], v[0:1]
	s_nop 1
	v_permlane32_swap_b32_e32 v230, v232
	v_permlane32_swap_b32_e32 v231, v233
	ds_write_b128 v206, v[230:233] offset:480
	ds_read_b128 v[96:99], v207
	ds_read_b128 v[100:103], v207 offset:1056
	ds_read_b128 v[104:107], v207 offset:2112
	ds_read_b128 v[108:111], v207 offset:3168
	ds_read_b128 v[112:115], v207 offset:4224
	ds_read_b128 v[116:119], v207 offset:5280
	ds_read_b128 v[120:123], v207 offset:6336
	s_waitcnt lgkmcnt(8)
	ds_read_b128 v[124:127], v207 offset:7392
	ds_read_b128 v[148:151], v207 offset:8448
	ds_read_b128 v[152:155], v207 offset:9504
	ds_read_b128 v[156:159], v207 offset:10560
	ds_read_b128 v[160:163], v207 offset:11616
	ds_read_b128 v[164:167], v207 offset:12672
	ds_read_b128 v[168:171], v207 offset:13728
	ds_read_b128 v[172:175], v207 offset:14784
	s_waitcnt lgkmcnt(8)
	ds_read_b128 v[176:179], v207 offset:15840
	v_mov_b64_e32 v[180:181], v[184:185]
	global_store_dwordx4 v[180:181], v[96:99], off
	v_lshl_add_u64 v[180:181], v[180:181], 0, s[84:85]
	global_store_dwordx4 v[180:181], v[100:103], off
	v_lshl_add_u64 v[180:181], v[180:181], 0, s[84:85]
	global_store_dwordx4 v[180:181], v[104:107], off
	v_lshl_add_u64 v[180:181], v[180:181], 0, s[84:85]
	global_store_dwordx4 v[180:181], v[108:111], off
	v_lshl_add_u64 v[180:181], v[180:181], 0, s[84:85]
	global_store_dwordx4 v[180:181], v[112:115], off
	v_lshl_add_u64 v[180:181], v[180:181], 0, s[84:85]
	global_store_dwordx4 v[180:181], v[116:119], off
	v_lshl_add_u64 v[180:181], v[180:181], 0, s[84:85]
	global_store_dwordx4 v[180:181], v[120:123], off
	v_lshl_add_u64 v[180:181], v[180:181], 0, s[84:85]
	s_waitcnt lgkmcnt(8)
	global_store_dwordx4 v[180:181], v[124:127], off
	v_lshl_add_u64 v[180:181], v[180:181], 0, s[84:85]
	s_waitcnt lgkmcnt(7)
	global_store_dwordx4 v[180:181], v[148:151], off
	v_lshl_add_u64 v[180:181], v[180:181], 0, s[84:85]
	s_waitcnt lgkmcnt(6)
	global_store_dwordx4 v[180:181], v[152:155], off
	v_lshl_add_u64 v[180:181], v[180:181], 0, s[84:85]
	s_waitcnt lgkmcnt(5)
	global_store_dwordx4 v[180:181], v[156:159], off
	v_lshl_add_u64 v[180:181], v[180:181], 0, s[84:85]
	s_waitcnt lgkmcnt(4)
	global_store_dwordx4 v[180:181], v[160:163], off
	v_lshl_add_u64 v[180:181], v[180:181], 0, s[84:85]
	s_waitcnt lgkmcnt(3)
	global_store_dwordx4 v[180:181], v[164:167], off
	v_lshl_add_u64 v[180:181], v[180:181], 0, s[84:85]
	s_waitcnt lgkmcnt(2)
	global_store_dwordx4 v[180:181], v[168:171], off
	v_lshl_add_u64 v[180:181], v[180:181], 0, s[84:85]
	s_waitcnt lgkmcnt(1)
	global_store_dwordx4 v[180:181], v[172:175], off
	v_lshl_add_u64 v[180:181], v[180:181], 0, s[84:85]
	s_waitcnt lgkmcnt(0)
	global_store_dwordx4 v[180:181], v[176:179], off
	s_cbranch_scc1 .LBB0_700
